# final f32 output stores of the last fused GEMM epilogue carry the nt (streaming) hint: the output is never re-read, so it no longer displaces the hidden activations the second round still has to read
# speedup vs baseline: 1.0037x; 1.0037x over previous
; DI unsigned pk_bf16(float lo, float hi) { f32x2 v = {lo, hi}; bf16x2_t b = __builtin_convertvector(v, bf16x2_t); return __builtin_bit_cast(unsigned, b); }
; DI float bflo(unsigned w) { return __uint_as_float(w << 16); }
; DI float bfhi(unsigned w) { return __uint_as_float(w & 0xffff0000u); }
;     __device__ __forceinline__ void fused(f32x4 (&acc)[2][2][4][2], const pg8::Unit& u, int wr, int wc, int fr, int fq, PG8_LAS unsigned char* lds, int wid, int lane) const {
;     ...
;         const int colb = u.pn * 256 + wc * 32 + 8 * fq;
;         f32x4 gv[2][2];
; #pragma unroll
;         for (int bj = 0; bj < 2; ++bj)
; #pragma unroll
;             for (int n = 0; n < 2; ++n) gv[bj][n] = *(const f32x4*)(gA + colb + bj * 128 + 4 * n);
; #pragma unroll
;         for (int ai = 0; ai < 2; ++ai)
; #pragma unroll
;             for (int m = 0; m < 4; ++m) {
;                 const int rl = ai * 128 + wr * 64 + m * 16 + fr; const size_t row = (size_t)u.pm * 256 + rl;
;                 const float rm = 1.f / sqrtf(__hip_atomic_load(ssqm + row, __ATOMIC_RELAXED, __HIP_MEMORY_SCOPE_AGENT) * (1.f / DM) + RMS_EPS);
;                 float sh = 0.f;
; #pragma unroll
;                 for (int bj = 0; bj < 2; ++bj) {
;                     const size_t off = row * DM + colb + bj * 128;
;                     f32x4 h0, h1;
;                     if (IN16) { const u32x4 hw = *(const u32x4*)((const bf16_t*)hin + off); h0 = (f32x4){bflo(hw.x), bfhi(hw.x), bflo(hw.y), bfhi(hw.y)}; h1 = (f32x4){bflo(hw.z), bfhi(hw.z), bflo(hw.w), bfhi(hw.w)}; }
;                     else { h0 = *(const f32x4*)((const float*)hin + off); h1 = *(const f32x4*)((const float*)hin + off + 4); }
;                     h0 = h0 + acc[ai][bj][m][0] * rm * gv[bj][0]; h1 = h1 + acc[ai][bj][m][1] * rm * gv[bj][1];
;                     sh += ((h0[0] * h0[0] + h0[1] * h0[1]) + (h0[2] * h0[2] + h0[3] * h0[3])) + ((h1[0] * h1[0] + h1[1] * h1[1]) + (h1[2] * h1[2] + h1[3] * h1[3]));
;                     if (OUT16) { u32x4 w; w.x = pk_bf16(h0[0], h0[1]); w.y = pk_bf16(h0[2], h0[3]); w.z = pk_bf16(h1[0], h1[1]); w.w = pk_bf16(h1[2], h1[3]); *(u32x4*)((bf16_t*)hout + off) = w; }
;                     else { *(f32x4*)((float*)hout + off) = h0; *(f32x4*)((float*)hout + off + 4) = h1; }
.LBB0_1629:
	s_or_b64 exec, exec, s[2:3]
	s_lshl_b32 s2, s33, 5
	s_lshl_b32 s3, s30, 8
	s_or_b32 s2, s3, s2
	v_or_b32_e32 v154, s2, v156
	s_lshl_b64 s[10:11], s[0:1], 8
	v_mov_b32_e32 v153, 0
	v_ashrrev_i32_e32 v155, 31, v154
	v_lshl_add_u64 v[164:165], s[10:11], 0, v[152:153]
	v_lshl_add_u64 v[116:117], v[154:155], 2, s[8:9]
	v_lshl_add_u64 v[166:167], v[164:165], 2, s[6:7]
	s_barrier
	global_load_dwordx4 v[120:123], v[116:117], off offset:16
	global_load_dwordx4 v[124:127], v[116:117], off
	global_load_dwordx4 v[108:111], v[116:117], off offset:528
	s_nop 0
	global_load_dwordx4 v[116:119], v[116:117], off offset:512
	v_lshlrev_b64 v[164:165], 10, v[164:165]
	global_load_dword v149, v[166:167], off sc1
	v_lshl_add_u64 v[168:169], v[164:165], 0, v[154:155]
	v_lshlrev_b64 v[170:171], 1, v[168:169]
	v_lshl_add_u64 v[164:165], s[4:5], 0, v[170:171]
	global_load_dwordx4 v[164:167], v[164:165], off
	v_mov_b32_e32 v147, 0x358637bd
	s_mov_b32 s2, 0xf800000
	v_mov_b32_e32 v145, 0x260
	v_readlane_b32 s12, v251, 0
	v_readlane_b32 s14, v251, 2
	v_readlane_b32 s15, v251, 3
	v_or_b32_e32 v170, 0x100, v170
	v_lshl_add_u64 v[170:171], s[4:5], 0, v[170:171]
	v_lshl_add_u64 v[168:169], v[168:169], 2, s[14:15]
	v_readlane_b32 s13, v251, 1
	s_waitcnt vmcnt(1)
	v_fmamk_f32 v149, v149, 0x3a800000, v147
	v_mul_f32_e32 v151, 0x4f800000, v149
	v_cmp_gt_f32_e32 vcc, s2, v149
	s_waitcnt vmcnt(0)
	v_lshlrev_b32_e32 v172, 16, v164
	v_cndmask_b32_e32 v149, v149, v151, vcc
	v_sqrt_f32_e32 v151, v149
	v_and_b32_e32 v173, 0xffff0000, v164
	v_lshlrev_b32_e32 v164, 16, v165
	v_and_b32_e32 v165, 0xffff0000, v165
	v_add_u32_e32 v176, -1, v151
	v_add_u32_e32 v177, 1, v151
	v_fma_f32 v178, -v176, v151, v149
	v_fma_f32 v179, -v177, v151, v149
	v_cmp_ge_f32_e64 s[0:1], 0, v178
	v_lshlrev_b32_e32 v174, 16, v166
	v_and_b32_e32 v175, 0xffff0000, v166
	v_cndmask_b32_e64 v151, v151, v176, s[0:1]
	v_cmp_lt_f32_e64 s[0:1], 0, v179
	v_lshlrev_b32_e32 v166, 16, v167
	v_and_b32_e32 v167, 0xffff0000, v167
	v_cndmask_b32_e64 v151, v151, v177, s[0:1]
	v_mul_f32_e32 v176, 0x37800000, v151
	v_cndmask_b32_e32 v151, v151, v176, vcc
	v_cmp_class_f32_e32 vcc, v149, v145
	s_nop 1
	v_cndmask_b32_e32 v149, v151, v149, vcc
	v_div_scale_f32 v151, s[0:1], v149, v149, 1.0
	v_rcp_f32_e32 v176, v151
	v_div_scale_f32 v177, vcc, 1.0, v149, 1.0
	v_fma_f32 v178, -v151, v176, 1.0
	v_fmac_f32_e32 v176, v178, v176
	v_mul_f32_e32 v178, v177, v176
	v_fma_f32 v179, -v151, v178, v177
	v_fmac_f32_e32 v178, v179, v176
	v_fma_f32 v151, -v151, v178, v177
	v_div_fmas_f32 v151, v151, v176, v178
	v_div_fixup_f32 v176, v151, v149, 1.0
	v_pk_mul_f32 v[140:141], v[140:141], v[176:177] op_sel_hi:[1,0]
	v_pk_mul_f32 v[142:143], v[142:143], v[176:177] op_sel_hi:[1,0]
	v_pk_mul_f32 v[178:179], v[136:137], v[176:177] op_sel_hi:[1,0]
	v_pk_mul_f32 v[180:181], v[138:139], v[176:177] op_sel_hi:[1,0]
	v_pk_fma_f32 v[138:139], v[126:127], v[142:143], v[164:165]
	v_pk_fma_f32 v[136:137], v[124:125], v[140:141], v[172:173]
	v_pk_fma_f32 v[142:143], v[122:123], v[180:181], v[166:167]
	v_pk_fma_f32 v[140:141], v[120:121], v[178:179], v[174:175]
	global_store_dwordx4 v[168:169], v[136:139], off nt
	global_store_dwordx4 v[168:169], v[140:143], off offset:16 nt
	global_load_dwordx4 v[136:139], v[170:171], off
	v_pk_mul_f32 v[132:133], v[132:133], v[176:177] op_sel_hi:[1,0]
	v_or_b32_e32 v140, 16, v152
	v_mov_b32_e32 v141, v153
	v_lshl_add_u64 v[140:141], s[10:11], 0, v[140:141]
	v_lshl_add_u64 v[142:143], v[140:141], 2, s[6:7]
	v_lshlrev_b64 v[140:141], 10, v[140:141]
	v_pk_mul_f32 v[134:135], v[134:135], v[176:177] op_sel_hi:[1,0]
	v_pk_mul_f32 v[170:171], v[128:129], v[176:177] op_sel_hi:[1,0]
	v_pk_mul_f32 v[172:173], v[130:131], v[176:177] op_sel_hi:[1,0]
	v_lshl_add_u64 v[140:141], v[140:141], 0, v[154:155]
	v_lshlrev_b64 v[164:165], 1, v[140:141]
	v_lshl_add_u64 v[166:167], s[4:5], 0, v[164:165]
	v_or_b32_e32 v164, 0x100, v164
	s_waitcnt vmcnt(0)
	v_lshlrev_b32_e32 v128, 16, v136
	v_and_b32_e32 v129, 0xffff0000, v136
	v_lshlrev_b32_e32 v130, 16, v137
	v_and_b32_e32 v131, 0xffff0000, v137
	v_lshlrev_b32_e32 v136, 16, v138
	v_and_b32_e32 v137, 0xffff0000, v138
	v_lshlrev_b32_e32 v138, 16, v139
	v_and_b32_e32 v139, 0xffff0000, v139
	v_pk_fma_f32 v[130:131], v[118:119], v[134:135], v[130:131]
	v_pk_fma_f32 v[128:129], v[116:117], v[132:133], v[128:129]
	v_pk_fma_f32 v[134:135], v[110:111], v[172:173], v[138:139]
	v_pk_fma_f32 v[132:133], v[108:109], v[170:171], v[136:137]
	global_store_dwordx4 v[168:169], v[128:131], off offset:512 nt
	global_store_dwordx4 v[168:169], v[132:135], off offset:528 nt
	global_load_dword v136, v[142:143], off sc1
	s_nop 0
	global_load_dwordx4 v[128:131], v[166:167], off
	v_lshl_add_u64 v[132:133], v[140:141], 2, s[14:15]
	v_lshl_add_u64 v[134:135], s[4:5], 0, v[164:165]
	s_waitcnt vmcnt(1)
	v_fmamk_f32 v138, v136, 0x3a800000, v147
	v_mul_f32_e32 v139, 0x4f800000, v138
	v_cmp_gt_f32_e32 vcc, s2, v138
	s_waitcnt vmcnt(0)
; DI unsigned pk_bf16(float lo, float hi) { f32x2 v = {lo, hi}; bf16x2_t b = __builtin_convertvector(v, bf16x2_t); return __builtin_bit_cast(unsigned, b); }
; DI float bflo(unsigned w) { return __uint_as_float(w << 16); }
; DI float bfhi(unsigned w) { return __uint_as_float(w & 0xffff0000u); }
;     __device__ __forceinline__ void fused(f32x4 (&acc)[2][2][4][2], const pg8::Unit& u, int wr, int wc, int fr, int fq, PG8_LAS unsigned char* lds, int wid, int lane) const {
;     ...
;                 const int rl = ai * 128 + wr * 64 + m * 16 + fr; const size_t row = (size_t)u.pm * 256 + rl;
;                 const float rm = 1.f / sqrtf(__hip_atomic_load(ssqm + row, __ATOMIC_RELAXED, __HIP_MEMORY_SCOPE_AGENT) * (1.f / DM) + RMS_EPS);
;                 float sh = 0.f;
; #pragma unroll
;                 for (int bj = 0; bj < 2; ++bj) {
;                     const size_t off = row * DM + colb + bj * 128;
;                     f32x4 h0, h1;
;                     if (IN16) { const u32x4 hw = *(const u32x4*)((const bf16_t*)hin + off); h0 = (f32x4){bflo(hw.x), bfhi(hw.x), bflo(hw.y), bfhi(hw.y)}; h1 = (f32x4){bflo(hw.z), bfhi(hw.z), bflo(hw.w), bfhi(hw.w)}; }
;                     else { h0 = *(const f32x4*)((const float*)hin + off); h1 = *(const f32x4*)((const float*)hin + off + 4); }
;                     h0 = h0 + acc[ai][bj][m][0] * rm * gv[bj][0]; h1 = h1 + acc[ai][bj][m][1] * rm * gv[bj][1];
;                     sh += ((h0[0] * h0[0] + h0[1] * h0[1]) + (h0[2] * h0[2] + h0[3] * h0[3])) + ((h1[0] * h1[0] + h1[1] * h1[1]) + (h1[2] * h1[2] + h1[3] * h1[3]));
;                     if (OUT16) { u32x4 w; w.x = pk_bf16(h0[0], h0[1]); w.y = pk_bf16(h0[2], h0[3]); w.z = pk_bf16(h1[0], h1[1]); w.w = pk_bf16(h1[2], h1[3]); *(u32x4*)((bf16_t*)hout + off) = w; }
;                     else { *(f32x4*)((float*)hout + off) = h0; *(f32x4*)((float*)hout + off + 4) = h1; }
	v_lshlrev_b32_e32 v136, 16, v128
	v_and_b32_e32 v137, 0xffff0000, v128
	v_cndmask_b32_e32 v140, v138, v139, vcc
	v_sqrt_f32_e32 v141, v140
	v_lshlrev_b32_e32 v128, 16, v129
	v_and_b32_e32 v129, 0xffff0000, v129
	v_lshlrev_b32_e32 v138, 16, v130
	v_add_u32_e32 v142, -1, v141
	v_add_u32_e32 v143, 1, v141
	v_fma_f32 v149, -v142, v141, v140
	v_fma_f32 v151, -v143, v141, v140
	v_cmp_ge_f32_e64 s[0:1], 0, v149
	v_and_b32_e32 v139, 0xffff0000, v130
	v_lshlrev_b32_e32 v130, 16, v131
	v_cndmask_b32_e64 v141, v141, v142, s[0:1]
	v_cmp_lt_f32_e64 s[0:1], 0, v151
	v_and_b32_e32 v131, 0xffff0000, v131
	s_nop 0
	v_cndmask_b32_e64 v141, v141, v143, s[0:1]
	v_mul_f32_e32 v142, 0x37800000, v141
	v_cndmask_b32_e32 v141, v141, v142, vcc
	v_cmp_class_f32_e32 vcc, v140, v145
	s_nop 1
	v_cndmask_b32_e32 v140, v141, v140, vcc
	v_div_scale_f32 v141, s[0:1], v140, v140, 1.0
	v_rcp_f32_e32 v142, v141
	v_div_scale_f32 v143, vcc, 1.0, v140, 1.0
	v_fma_f32 v149, -v141, v142, 1.0
	v_fmac_f32_e32 v142, v149, v142
	v_mul_f32_e32 v149, v143, v142
	v_fma_f32 v151, -v141, v149, v143
	v_fmac_f32_e32 v149, v151, v142
	v_fma_f32 v141, -v141, v149, v143
	v_div_fmas_f32 v141, v141, v142, v149
	v_div_fixup_f32 v140, v141, v140, 1.0
	v_pk_mul_f32 v[112:113], v[112:113], v[140:141] op_sel_hi:[1,0]
	v_pk_mul_f32 v[114:115], v[114:115], v[140:141] op_sel_hi:[1,0]
	v_pk_mul_f32 v[142:143], v[104:105], v[140:141] op_sel_hi:[1,0]
	v_pk_mul_f32 v[164:165], v[106:107], v[140:141] op_sel_hi:[1,0]
	v_pk_fma_f32 v[106:107], v[126:127], v[114:115], v[128:129]
	v_pk_fma_f32 v[104:105], v[124:125], v[112:113], v[136:137]
	v_pk_fma_f32 v[114:115], v[122:123], v[164:165], v[130:131]
	v_pk_fma_f32 v[112:113], v[120:121], v[142:143], v[138:139]
	global_store_dwordx4 v[132:133], v[104:107], off nt
	global_store_dwordx4 v[132:133], v[112:115], off offset:16 nt
	global_load_dwordx4 v[104:107], v[134:135], off
	v_pk_mul_f32 v[100:101], v[100:101], v[140:141] op_sel_hi:[1,0]
	v_or_b32_e32 v112, 32, v152
	v_mov_b32_e32 v113, v153
	v_lshl_add_u64 v[112:113], s[10:11], 0, v[112:113]
	v_lshl_add_u64 v[114:115], v[112:113], 2, s[6:7]
	v_lshlrev_b64 v[112:113], 10, v[112:113]
	v_pk_mul_f32 v[102:103], v[102:103], v[140:141] op_sel_hi:[1,0]
	v_pk_mul_f32 v[134:135], v[96:97], v[140:141] op_sel_hi:[1,0]
	v_pk_mul_f32 v[136:137], v[98:99], v[140:141] op_sel_hi:[1,0]
	v_lshl_add_u64 v[112:113], v[112:113], 0, v[154:155]
	v_lshlrev_b64 v[128:129], 1, v[112:113]
	v_lshl_add_u64 v[130:131], s[4:5], 0, v[128:129]
	v_or_b32_e32 v128, 0x100, v128
	s_waitcnt vmcnt(0)
	v_lshlrev_b32_e32 v96, 16, v104
	v_and_b32_e32 v97, 0xffff0000, v104
	v_lshlrev_b32_e32 v98, 16, v105
	v_and_b32_e32 v99, 0xffff0000, v105
	v_lshlrev_b32_e32 v104, 16, v106
	v_and_b32_e32 v105, 0xffff0000, v106
	v_lshlrev_b32_e32 v106, 16, v107
	v_and_b32_e32 v107, 0xffff0000, v107
	v_pk_fma_f32 v[98:99], v[118:119], v[102:103], v[98:99]
	v_pk_fma_f32 v[96:97], v[116:117], v[100:101], v[96:97]
	v_pk_fma_f32 v[102:103], v[110:111], v[136:137], v[106:107]
	v_pk_fma_f32 v[100:101], v[108:109], v[134:135], v[104:105]
	global_store_dwordx4 v[132:133], v[96:99], off offset:512 nt
	global_store_dwordx4 v[132:133], v[100:103], off offset:528 nt
	global_load_dword v104, v[114:115], off sc1
	s_nop 0
	global_load_dwordx4 v[96:99], v[130:131], off
	v_lshl_add_u64 v[100:101], v[112:113], 2, s[14:15]
	v_lshl_add_u64 v[102:103], s[4:5], 0, v[128:129]
	s_waitcnt vmcnt(1)
	v_fmamk_f32 v106, v104, 0x3a800000, v147
	v_mul_f32_e32 v107, 0x4f800000, v106
	v_cmp_gt_f32_e32 vcc, s2, v106
	s_waitcnt vmcnt(0)
	v_lshlrev_b32_e32 v104, 16, v96
	v_and_b32_e32 v105, 0xffff0000, v96
	v_cndmask_b32_e32 v112, v106, v107, vcc
	v_sqrt_f32_e32 v113, v112
	v_lshlrev_b32_e32 v96, 16, v97
	v_and_b32_e32 v97, 0xffff0000, v97
	v_lshlrev_b32_e32 v106, 16, v98
	v_add_u32_e32 v114, -1, v113
	v_add_u32_e32 v115, 1, v113
	v_fma_f32 v128, -v114, v113, v112
	v_fma_f32 v129, -v115, v113, v112
	v_cmp_ge_f32_e64 s[0:1], 0, v128
	v_and_b32_e32 v107, 0xffff0000, v98
	v_lshlrev_b32_e32 v98, 16, v99
	v_cndmask_b32_e64 v113, v113, v114, s[0:1]
	v_cmp_lt_f32_e64 s[0:1], 0, v129
	v_and_b32_e32 v99, 0xffff0000, v99
	s_nop 0
	v_cndmask_b32_e64 v113, v113, v115, s[0:1]
	v_mul_f32_e32 v114, 0x37800000, v113
	v_cndmask_b32_e32 v113, v113, v114, vcc
	v_cmp_class_f32_e32 vcc, v112, v145
	s_nop 1
	v_cndmask_b32_e32 v112, v113, v112, vcc
	v_div_scale_f32 v113, s[0:1], v112, v112, 1.0
	v_rcp_f32_e32 v114, v113
	v_div_scale_f32 v115, vcc, 1.0, v112, 1.0
	v_fma_f32 v128, -v113, v114, 1.0
	v_fmac_f32_e32 v114, v128, v114
	v_mul_f32_e32 v128, v115, v114
	v_fma_f32 v129, -v113, v128, v115
	v_fmac_f32_e32 v128, v129, v114
	v_fma_f32 v113, -v113, v128, v115
	v_div_fmas_f32 v113, v113, v114, v128
	v_div_fixup_f32 v112, v113, v112, 1.0
	v_pk_mul_f32 v[92:93], v[92:93], v[112:113] op_sel_hi:[1,0]
	v_pk_mul_f32 v[94:95], v[94:95], v[112:113] op_sel_hi:[1,0]
	v_pk_mul_f32 v[114:115], v[88:89], v[112:113] op_sel_hi:[1,0]
	v_pk_mul_f32 v[128:129], v[90:91], v[112:113] op_sel_hi:[1,0]
	v_pk_fma_f32 v[90:91], v[126:127], v[94:95], v[96:97]
	v_pk_fma_f32 v[88:89], v[124:125], v[92:93], v[104:105]
	v_pk_fma_f32 v[94:95], v[122:123], v[128:129], v[98:99]
	v_pk_fma_f32 v[92:93], v[120:121], v[114:115], v[106:107]
	global_store_dwordx4 v[100:101], v[88:91], off nt
	global_store_dwordx4 v[100:101], v[92:95], off offset:16 nt
	global_load_dwordx4 v[88:91], v[102:103], off
	v_pk_mul_f32 v[84:85], v[84:85], v[112:113] op_sel_hi:[1,0]
	v_or_b32_e32 v92, 48, v152
	v_mov_b32_e32 v93, v153
	v_lshl_add_u64 v[92:93], s[10:11], 0, v[92:93]
	v_lshl_add_u64 v[94:95], v[92:93], 2, s[6:7]
	v_lshlrev_b64 v[92:93], 10, v[92:93]
	v_pk_mul_f32 v[86:87], v[86:87], v[112:113] op_sel_hi:[1,0]
	v_pk_mul_f32 v[102:103], v[80:81], v[112:113] op_sel_hi:[1,0]
	v_pk_mul_f32 v[104:105], v[82:83], v[112:113] op_sel_hi:[1,0]
	v_lshl_add_u64 v[92:93], v[92:93], 0, v[154:155]
	v_lshlrev_b64 v[96:97], 1, v[92:93]
	v_lshl_add_u64 v[98:99], s[4:5], 0, v[96:97]
	v_or_b32_e32 v96, 0x100, v96
	s_waitcnt vmcnt(0)
; DI unsigned pk_bf16(float lo, float hi) { f32x2 v = {lo, hi}; bf16x2_t b = __builtin_convertvector(v, bf16x2_t); return __builtin_bit_cast(unsigned, b); }
; DI float bflo(unsigned w) { return __uint_as_float(w << 16); }
; DI float bfhi(unsigned w) { return __uint_as_float(w & 0xffff0000u); }
;     __device__ __forceinline__ void fused(f32x4 (&acc)[2][2][4][2], const pg8::Unit& u, int wr, int wc, int fr, int fq, PG8_LAS unsigned char* lds, int wid, int lane) const {
;     ...
;                 const int rl = ai * 128 + wr * 64 + m * 16 + fr; const size_t row = (size_t)u.pm * 256 + rl;
;                 const float rm = 1.f / sqrtf(__hip_atomic_load(ssqm + row, __ATOMIC_RELAXED, __HIP_MEMORY_SCOPE_AGENT) * (1.f / DM) + RMS_EPS);
;                 float sh = 0.f;
; #pragma unroll
;                 for (int bj = 0; bj < 2; ++bj) {
;                     const size_t off = row * DM + colb + bj * 128;
;                     f32x4 h0, h1;
;                     if (IN16) { const u32x4 hw = *(const u32x4*)((const bf16_t*)hin + off); h0 = (f32x4){bflo(hw.x), bfhi(hw.x), bflo(hw.y), bfhi(hw.y)}; h1 = (f32x4){bflo(hw.z), bfhi(hw.z), bflo(hw.w), bfhi(hw.w)}; }
;                     else { h0 = *(const f32x4*)((const float*)hin + off); h1 = *(const f32x4*)((const float*)hin + off + 4); }
;                     h0 = h0 + acc[ai][bj][m][0] * rm * gv[bj][0]; h1 = h1 + acc[ai][bj][m][1] * rm * gv[bj][1];
;                     sh += ((h0[0] * h0[0] + h0[1] * h0[1]) + (h0[2] * h0[2] + h0[3] * h0[3])) + ((h1[0] * h1[0] + h1[1] * h1[1]) + (h1[2] * h1[2] + h1[3] * h1[3]));
;                     if (OUT16) { u32x4 w; w.x = pk_bf16(h0[0], h0[1]); w.y = pk_bf16(h0[2], h0[3]); w.z = pk_bf16(h1[0], h1[1]); w.w = pk_bf16(h1[2], h1[3]); *(u32x4*)((bf16_t*)hout + off) = w; }
;                     else { *(f32x4*)((float*)hout + off) = h0; *(f32x4*)((float*)hout + off + 4) = h1; }
	v_lshlrev_b32_e32 v80, 16, v88
	v_and_b32_e32 v81, 0xffff0000, v88
	v_lshlrev_b32_e32 v82, 16, v89
	v_and_b32_e32 v83, 0xffff0000, v89
	v_lshlrev_b32_e32 v88, 16, v90
	v_and_b32_e32 v89, 0xffff0000, v90
	v_lshlrev_b32_e32 v90, 16, v91
	v_and_b32_e32 v91, 0xffff0000, v91
	v_pk_fma_f32 v[82:83], v[118:119], v[86:87], v[82:83]
	v_pk_fma_f32 v[80:81], v[116:117], v[84:85], v[80:81]
	v_pk_fma_f32 v[86:87], v[110:111], v[104:105], v[90:91]
	v_pk_fma_f32 v[84:85], v[108:109], v[102:103], v[88:89]
	global_store_dwordx4 v[100:101], v[80:83], off offset:512 nt
	global_store_dwordx4 v[100:101], v[84:87], off offset:528 nt
	global_load_dword v88, v[94:95], off sc1
	s_nop 0
	global_load_dwordx4 v[80:83], v[98:99], off
	v_lshl_add_u64 v[84:85], v[92:93], 2, s[14:15]
	v_lshl_add_u64 v[86:87], s[4:5], 0, v[96:97]
	s_waitcnt vmcnt(1)
	v_fmamk_f32 v90, v88, 0x3a800000, v147
	v_mul_f32_e32 v91, 0x4f800000, v90
	v_cmp_gt_f32_e32 vcc, s2, v90
	s_waitcnt vmcnt(0)
	v_lshlrev_b32_e32 v88, 16, v80
	v_and_b32_e32 v89, 0xffff0000, v80
	v_cndmask_b32_e32 v92, v90, v91, vcc
	v_sqrt_f32_e32 v93, v92
	v_lshlrev_b32_e32 v80, 16, v81
	v_and_b32_e32 v81, 0xffff0000, v81
	v_lshlrev_b32_e32 v90, 16, v82
	v_add_u32_e32 v94, -1, v93
	v_add_u32_e32 v95, 1, v93
	v_fma_f32 v96, -v94, v93, v92
	v_fma_f32 v97, -v95, v93, v92
	v_cmp_ge_f32_e64 s[0:1], 0, v96
	v_and_b32_e32 v91, 0xffff0000, v82
	v_lshlrev_b32_e32 v82, 16, v83
	v_cndmask_b32_e64 v93, v93, v94, s[0:1]
	v_cmp_lt_f32_e64 s[0:1], 0, v97
	v_and_b32_e32 v83, 0xffff0000, v83
	s_nop 0
	v_cndmask_b32_e64 v93, v93, v95, s[0:1]
	v_mul_f32_e32 v94, 0x37800000, v93
	v_cndmask_b32_e32 v93, v93, v94, vcc
	v_cmp_class_f32_e32 vcc, v92, v145
	s_nop 1
	v_cndmask_b32_e32 v92, v93, v92, vcc
	v_div_scale_f32 v93, s[0:1], v92, v92, 1.0
	v_rcp_f32_e32 v94, v93
	v_div_scale_f32 v95, vcc, 1.0, v92, 1.0
	v_fma_f32 v96, -v93, v94, 1.0
	v_fmac_f32_e32 v94, v96, v94
	v_mul_f32_e32 v96, v95, v94
	v_fma_f32 v97, -v93, v96, v95
	v_fmac_f32_e32 v96, v97, v94
	v_fma_f32 v93, -v93, v96, v95
	v_div_fmas_f32 v93, v93, v94, v96
	v_div_fixup_f32 v92, v93, v92, 1.0
	v_pk_mul_f32 v[76:77], v[76:77], v[92:93] op_sel_hi:[1,0]
	v_pk_mul_f32 v[78:79], v[78:79], v[92:93] op_sel_hi:[1,0]
	v_pk_mul_f32 v[94:95], v[72:73], v[92:93] op_sel_hi:[1,0]
	v_pk_mul_f32 v[96:97], v[74:75], v[92:93] op_sel_hi:[1,0]
	v_pk_fma_f32 v[74:75], v[126:127], v[78:79], v[80:81]
	v_pk_fma_f32 v[72:73], v[124:125], v[76:77], v[88:89]
	v_pk_fma_f32 v[78:79], v[122:123], v[96:97], v[82:83]
	v_pk_fma_f32 v[76:77], v[120:121], v[94:95], v[90:91]
	global_store_dwordx4 v[84:85], v[72:75], off nt
	global_store_dwordx4 v[84:85], v[76:79], off offset:16 nt
	global_load_dwordx4 v[72:75], v[86:87], off
	v_pk_mul_f32 v[68:69], v[68:69], v[92:93] op_sel_hi:[1,0]
	v_add_u32_e32 v76, 0x80, v152
	v_mov_b32_e32 v77, v153
	v_lshl_add_u64 v[76:77], s[10:11], 0, v[76:77]
	v_lshl_add_u64 v[78:79], v[76:77], 2, s[6:7]
	v_lshlrev_b64 v[76:77], 10, v[76:77]
	v_pk_mul_f32 v[70:71], v[70:71], v[92:93] op_sel_hi:[1,0]
	v_pk_mul_f32 v[86:87], v[64:65], v[92:93] op_sel_hi:[1,0]
	v_pk_mul_f32 v[88:89], v[66:67], v[92:93] op_sel_hi:[1,0]
	v_lshl_add_u64 v[76:77], v[76:77], 0, v[154:155]
	v_lshlrev_b64 v[80:81], 1, v[76:77]
	v_lshl_add_u64 v[82:83], s[4:5], 0, v[80:81]
	v_or_b32_e32 v80, 0x100, v80
	s_waitcnt vmcnt(0)
	v_lshlrev_b32_e32 v64, 16, v72
	v_and_b32_e32 v65, 0xffff0000, v72
	v_lshlrev_b32_e32 v66, 16, v73
	v_and_b32_e32 v67, 0xffff0000, v73
	v_lshlrev_b32_e32 v72, 16, v74
	v_and_b32_e32 v73, 0xffff0000, v74
	v_lshlrev_b32_e32 v74, 16, v75
	v_and_b32_e32 v75, 0xffff0000, v75
	v_pk_fma_f32 v[66:67], v[118:119], v[70:71], v[66:67]
	v_pk_fma_f32 v[64:65], v[116:117], v[68:69], v[64:65]
	v_pk_fma_f32 v[70:71], v[110:111], v[88:89], v[74:75]
	v_pk_fma_f32 v[68:69], v[108:109], v[86:87], v[72:73]
	global_store_dwordx4 v[84:85], v[64:67], off offset:512 nt
	global_store_dwordx4 v[84:85], v[68:71], off offset:528 nt
	global_load_dword v72, v[78:79], off sc1
	s_nop 0
	global_load_dwordx4 v[64:67], v[82:83], off
	v_lshl_add_u64 v[68:69], v[76:77], 2, s[14:15]
	v_lshl_add_u64 v[70:71], s[4:5], 0, v[80:81]
	s_waitcnt vmcnt(1)
	v_fmamk_f32 v74, v72, 0x3a800000, v147
	v_mul_f32_e32 v75, 0x4f800000, v74
	v_cmp_gt_f32_e32 vcc, s2, v74
	s_waitcnt vmcnt(0)
	v_lshlrev_b32_e32 v72, 16, v64
	v_and_b32_e32 v73, 0xffff0000, v64
	v_cndmask_b32_e32 v76, v74, v75, vcc
	v_sqrt_f32_e32 v77, v76
	v_lshlrev_b32_e32 v64, 16, v65
	v_and_b32_e32 v65, 0xffff0000, v65
	v_lshlrev_b32_e32 v74, 16, v66
	v_add_u32_e32 v78, -1, v77
	v_add_u32_e32 v79, 1, v77
	v_fma_f32 v80, -v78, v77, v76
	v_fma_f32 v81, -v79, v77, v76
	v_cmp_ge_f32_e64 s[0:1], 0, v80
	v_and_b32_e32 v75, 0xffff0000, v66
	v_lshlrev_b32_e32 v66, 16, v67
	v_cndmask_b32_e64 v77, v77, v78, s[0:1]
	v_cmp_lt_f32_e64 s[0:1], 0, v81
	v_and_b32_e32 v67, 0xffff0000, v67
	s_nop 0
	v_cndmask_b32_e64 v77, v77, v79, s[0:1]
	v_mul_f32_e32 v78, 0x37800000, v77
	v_cndmask_b32_e32 v77, v77, v78, vcc
	v_cmp_class_f32_e32 vcc, v76, v145
	s_nop 1
	v_cndmask_b32_e32 v76, v77, v76, vcc
	v_div_scale_f32 v77, s[0:1], v76, v76, 1.0
	v_rcp_f32_e32 v78, v77
	v_div_scale_f32 v79, vcc, 1.0, v76, 1.0
	v_fma_f32 v80, -v77, v78, 1.0
	v_fmac_f32_e32 v78, v80, v78
	v_mul_f32_e32 v80, v79, v78
	v_fma_f32 v81, -v77, v80, v79
	v_fmac_f32_e32 v80, v81, v78
	v_fma_f32 v77, -v77, v80, v79
	v_div_fmas_f32 v77, v77, v78, v80
	v_div_fixup_f32 v76, v77, v76, 1.0
	v_pk_mul_f32 v[60:61], v[60:61], v[76:77] op_sel_hi:[1,0]
	v_pk_mul_f32 v[62:63], v[62:63], v[76:77] op_sel_hi:[1,0]
	v_pk_mul_f32 v[78:79], v[56:57], v[76:77] op_sel_hi:[1,0]
	v_pk_mul_f32 v[80:81], v[58:59], v[76:77] op_sel_hi:[1,0]
	v_pk_fma_f32 v[58:59], v[126:127], v[62:63], v[64:65]
	v_pk_fma_f32 v[56:57], v[124:125], v[60:61], v[72:73]
	v_pk_fma_f32 v[62:63], v[122:123], v[80:81], v[66:67]
	v_pk_fma_f32 v[60:61], v[120:121], v[78:79], v[74:75]
	global_store_dwordx4 v[68:69], v[56:59], off nt
	global_store_dwordx4 v[68:69], v[60:63], off offset:16 nt
	global_load_dwordx4 v[56:59], v[70:71], off
	v_pk_mul_f32 v[52:53], v[52:53], v[76:77] op_sel_hi:[1,0]
	v_add_u32_e32 v60, 0x90, v152
	v_mov_b32_e32 v61, v153
	v_lshl_add_u64 v[60:61], s[10:11], 0, v[60:61]
	v_lshl_add_u64 v[62:63], v[60:61], 2, s[6:7]
	v_lshlrev_b64 v[60:61], 10, v[60:61]
	v_pk_mul_f32 v[54:55], v[54:55], v[76:77] op_sel_hi:[1,0]
	v_pk_mul_f32 v[70:71], v[48:49], v[76:77] op_sel_hi:[1,0]
	v_pk_mul_f32 v[72:73], v[50:51], v[76:77] op_sel_hi:[1,0]
	v_lshl_add_u64 v[60:61], v[60:61], 0, v[154:155]
	v_lshlrev_b64 v[64:65], 1, v[60:61]
	v_lshl_add_u64 v[66:67], s[4:5], 0, v[64:65]
	v_or_b32_e32 v64, 0x100, v64
	s_waitcnt vmcnt(0)
; DI unsigned pk_bf16(float lo, float hi) { f32x2 v = {lo, hi}; bf16x2_t b = __builtin_convertvector(v, bf16x2_t); return __builtin_bit_cast(unsigned, b); }
; DI float bflo(unsigned w) { return __uint_as_float(w << 16); }
; DI float bfhi(unsigned w) { return __uint_as_float(w & 0xffff0000u); }
;     __device__ __forceinline__ void fused(f32x4 (&acc)[2][2][4][2], const pg8::Unit& u, int wr, int wc, int fr, int fq, PG8_LAS unsigned char* lds, int wid, int lane) const {
;     ...
;                 const int rl = ai * 128 + wr * 64 + m * 16 + fr; const size_t row = (size_t)u.pm * 256 + rl;
;                 const float rm = 1.f / sqrtf(__hip_atomic_load(ssqm + row, __ATOMIC_RELAXED, __HIP_MEMORY_SCOPE_AGENT) * (1.f / DM) + RMS_EPS);
;                 float sh = 0.f;
; #pragma unroll
;                 for (int bj = 0; bj < 2; ++bj) {
;                     const size_t off = row * DM + colb + bj * 128;
;                     f32x4 h0, h1;
;                     if (IN16) { const u32x4 hw = *(const u32x4*)((const bf16_t*)hin + off); h0 = (f32x4){bflo(hw.x), bfhi(hw.x), bflo(hw.y), bfhi(hw.y)}; h1 = (f32x4){bflo(hw.z), bfhi(hw.z), bflo(hw.w), bfhi(hw.w)}; }
;                     else { h0 = *(const f32x4*)((const float*)hin + off); h1 = *(const f32x4*)((const float*)hin + off + 4); }
;                     h0 = h0 + acc[ai][bj][m][0] * rm * gv[bj][0]; h1 = h1 + acc[ai][bj][m][1] * rm * gv[bj][1];
;                     sh += ((h0[0] * h0[0] + h0[1] * h0[1]) + (h0[2] * h0[2] + h0[3] * h0[3])) + ((h1[0] * h1[0] + h1[1] * h1[1]) + (h1[2] * h1[2] + h1[3] * h1[3]));
;                     if (OUT16) { u32x4 w; w.x = pk_bf16(h0[0], h0[1]); w.y = pk_bf16(h0[2], h0[3]); w.z = pk_bf16(h1[0], h1[1]); w.w = pk_bf16(h1[2], h1[3]); *(u32x4*)((bf16_t*)hout + off) = w; }
;                     else { *(f32x4*)((float*)hout + off) = h0; *(f32x4*)((float*)hout + off + 4) = h1; }
	v_lshlrev_b32_e32 v48, 16, v56
	v_and_b32_e32 v49, 0xffff0000, v56
	v_lshlrev_b32_e32 v50, 16, v57
	v_and_b32_e32 v51, 0xffff0000, v57
	v_lshlrev_b32_e32 v56, 16, v58
	v_and_b32_e32 v57, 0xffff0000, v58
	v_lshlrev_b32_e32 v58, 16, v59
	v_and_b32_e32 v59, 0xffff0000, v59
	v_pk_fma_f32 v[50:51], v[118:119], v[54:55], v[50:51]
	v_pk_fma_f32 v[48:49], v[116:117], v[52:53], v[48:49]
	v_pk_fma_f32 v[54:55], v[110:111], v[72:73], v[58:59]
	v_pk_fma_f32 v[52:53], v[108:109], v[70:71], v[56:57]
	global_store_dwordx4 v[68:69], v[48:51], off offset:512 nt
	global_store_dwordx4 v[68:69], v[52:55], off offset:528 nt
	global_load_dword v56, v[62:63], off sc1
	s_nop 0
	global_load_dwordx4 v[48:51], v[66:67], off
	v_lshl_add_u64 v[52:53], v[60:61], 2, s[14:15]
	v_lshl_add_u64 v[54:55], s[4:5], 0, v[64:65]
	s_waitcnt vmcnt(1)
	v_fmamk_f32 v58, v56, 0x3a800000, v147
	v_mul_f32_e32 v59, 0x4f800000, v58
	v_cmp_gt_f32_e32 vcc, s2, v58
	s_waitcnt vmcnt(0)
	v_lshlrev_b32_e32 v56, 16, v48
	v_and_b32_e32 v57, 0xffff0000, v48
	v_cndmask_b32_e32 v60, v58, v59, vcc
	v_sqrt_f32_e32 v61, v60
	v_lshlrev_b32_e32 v48, 16, v49
	v_and_b32_e32 v49, 0xffff0000, v49
	v_lshlrev_b32_e32 v58, 16, v50
	v_add_u32_e32 v62, -1, v61
	v_add_u32_e32 v63, 1, v61
	v_fma_f32 v64, -v62, v61, v60
	v_fma_f32 v65, -v63, v61, v60
	v_cmp_ge_f32_e64 s[0:1], 0, v64
	v_and_b32_e32 v59, 0xffff0000, v50
	v_lshlrev_b32_e32 v50, 16, v51
	v_cndmask_b32_e64 v61, v61, v62, s[0:1]
	v_cmp_lt_f32_e64 s[0:1], 0, v65
	v_and_b32_e32 v51, 0xffff0000, v51
	s_nop 0
	v_cndmask_b32_e64 v61, v61, v63, s[0:1]
	v_mul_f32_e32 v62, 0x37800000, v61
	v_cndmask_b32_e32 v61, v61, v62, vcc
	v_cmp_class_f32_e32 vcc, v60, v145
	s_nop 1
	v_cndmask_b32_e32 v60, v61, v60, vcc
	v_div_scale_f32 v61, s[0:1], v60, v60, 1.0
	v_rcp_f32_e32 v62, v61
	v_div_scale_f32 v63, vcc, 1.0, v60, 1.0
	v_fma_f32 v64, -v61, v62, 1.0
	v_fmac_f32_e32 v62, v64, v62
	v_mul_f32_e32 v64, v63, v62
	v_fma_f32 v65, -v61, v64, v63
	v_fmac_f32_e32 v64, v65, v62
	v_fma_f32 v61, -v61, v64, v63
	v_div_fmas_f32 v61, v61, v62, v64
	v_div_fixup_f32 v60, v61, v60, 1.0
	v_pk_mul_f32 v[44:45], v[44:45], v[60:61] op_sel_hi:[1,0]
	v_pk_mul_f32 v[46:47], v[46:47], v[60:61] op_sel_hi:[1,0]
	v_pk_mul_f32 v[62:63], v[40:41], v[60:61] op_sel_hi:[1,0]
	v_pk_mul_f32 v[64:65], v[42:43], v[60:61] op_sel_hi:[1,0]
	v_pk_fma_f32 v[42:43], v[126:127], v[46:47], v[48:49]
	v_pk_fma_f32 v[40:41], v[124:125], v[44:45], v[56:57]
	v_pk_fma_f32 v[46:47], v[122:123], v[64:65], v[50:51]
	v_pk_fma_f32 v[44:45], v[120:121], v[62:63], v[58:59]
	global_store_dwordx4 v[52:53], v[40:43], off nt
	global_store_dwordx4 v[52:53], v[44:47], off offset:16 nt
	global_load_dwordx4 v[40:43], v[54:55], off
	v_pk_mul_f32 v[36:37], v[36:37], v[60:61] op_sel_hi:[1,0]
	v_add_u32_e32 v44, 0xa0, v152
	v_mov_b32_e32 v45, v153
	v_lshl_add_u64 v[44:45], s[10:11], 0, v[44:45]
	v_lshl_add_u64 v[46:47], v[44:45], 2, s[6:7]
	v_lshlrev_b64 v[44:45], 10, v[44:45]
	v_pk_mul_f32 v[38:39], v[38:39], v[60:61] op_sel_hi:[1,0]
	v_pk_mul_f32 v[54:55], v[32:33], v[60:61] op_sel_hi:[1,0]
	v_pk_mul_f32 v[56:57], v[34:35], v[60:61] op_sel_hi:[1,0]
	v_lshl_add_u64 v[44:45], v[44:45], 0, v[154:155]
	v_lshlrev_b64 v[48:49], 1, v[44:45]
	v_lshl_add_u64 v[50:51], s[4:5], 0, v[48:49]
	v_or_b32_e32 v48, 0x100, v48
	v_add_u32_e32 v152, 0xb0, v152
	s_waitcnt vmcnt(0)
	v_lshlrev_b32_e32 v32, 16, v40
	v_and_b32_e32 v33, 0xffff0000, v40
	v_lshlrev_b32_e32 v34, 16, v41
	v_and_b32_e32 v35, 0xffff0000, v41
	v_lshlrev_b32_e32 v40, 16, v42
	v_and_b32_e32 v41, 0xffff0000, v42
	v_lshlrev_b32_e32 v42, 16, v43
	v_and_b32_e32 v43, 0xffff0000, v43
	v_pk_fma_f32 v[34:35], v[118:119], v[38:39], v[34:35]
	v_pk_fma_f32 v[32:33], v[116:117], v[36:37], v[32:33]
	v_pk_fma_f32 v[38:39], v[110:111], v[56:57], v[42:43]
	v_pk_fma_f32 v[36:37], v[108:109], v[54:55], v[40:41]
	global_store_dwordx4 v[52:53], v[32:35], off offset:512 nt
	global_store_dwordx4 v[52:53], v[36:39], off offset:528 nt
	global_load_dword v40, v[46:47], off sc1
	s_nop 0
	global_load_dwordx4 v[32:35], v[50:51], off
	v_lshl_add_u64 v[36:37], v[44:45], 2, s[14:15]
	v_lshl_add_u64 v[38:39], s[4:5], 0, v[48:49]
	s_waitcnt vmcnt(1)
	v_fmamk_f32 v42, v40, 0x3a800000, v147
	v_mul_f32_e32 v43, 0x4f800000, v42
	v_cmp_gt_f32_e32 vcc, s2, v42
	s_waitcnt vmcnt(0)
; DI unsigned pk_bf16(float lo, float hi) { f32x2 v = {lo, hi}; bf16x2_t b = __builtin_convertvector(v, bf16x2_t); return __builtin_bit_cast(unsigned, b); }
; DI float bflo(unsigned w) { return __uint_as_float(w << 16); }
; DI float bfhi(unsigned w) { return __uint_as_float(w & 0xffff0000u); }
;     __device__ __forceinline__ void fused(f32x4 (&acc)[2][2][4][2], const pg8::Unit& u, int wr, int wc, int fr, int fq, PG8_LAS unsigned char* lds, int wid, int lane) const {
;     ...
;                 const int rl = ai * 128 + wr * 64 + m * 16 + fr; const size_t row = (size_t)u.pm * 256 + rl;
;                 const float rm = 1.f / sqrtf(__hip_atomic_load(ssqm + row, __ATOMIC_RELAXED, __HIP_MEMORY_SCOPE_AGENT) * (1.f / DM) + RMS_EPS);
;                 float sh = 0.f;
; #pragma unroll
;                 for (int bj = 0; bj < 2; ++bj) {
;                     const size_t off = row * DM + colb + bj * 128;
;                     f32x4 h0, h1;
;                     if (IN16) { const u32x4 hw = *(const u32x4*)((const bf16_t*)hin + off); h0 = (f32x4){bflo(hw.x), bfhi(hw.x), bflo(hw.y), bfhi(hw.y)}; h1 = (f32x4){bflo(hw.z), bfhi(hw.z), bflo(hw.w), bfhi(hw.w)}; }
;                     else { h0 = *(const f32x4*)((const float*)hin + off); h1 = *(const f32x4*)((const float*)hin + off + 4); }
;                     h0 = h0 + acc[ai][bj][m][0] * rm * gv[bj][0]; h1 = h1 + acc[ai][bj][m][1] * rm * gv[bj][1];
;                     sh += ((h0[0] * h0[0] + h0[1] * h0[1]) + (h0[2] * h0[2] + h0[3] * h0[3])) + ((h1[0] * h1[0] + h1[1] * h1[1]) + (h1[2] * h1[2] + h1[3] * h1[3]));
;                     if (OUT16) { u32x4 w; w.x = pk_bf16(h0[0], h0[1]); w.y = pk_bf16(h0[2], h0[3]); w.z = pk_bf16(h1[0], h1[1]); w.w = pk_bf16(h1[2], h1[3]); *(u32x4*)((bf16_t*)hout + off) = w; }
;                     else { *(f32x4*)((float*)hout + off) = h0; *(f32x4*)((float*)hout + off + 4) = h1; }
	v_lshlrev_b32_e32 v40, 16, v32
	v_and_b32_e32 v41, 0xffff0000, v32
	v_cndmask_b32_e32 v44, v42, v43, vcc
	v_sqrt_f32_e32 v45, v44
	v_lshlrev_b32_e32 v32, 16, v33
	v_and_b32_e32 v33, 0xffff0000, v33
	v_lshlrev_b32_e32 v42, 16, v34
	v_add_u32_e32 v46, -1, v45
	v_add_u32_e32 v47, 1, v45
	v_fma_f32 v48, -v46, v45, v44
	v_fma_f32 v49, -v47, v45, v44
	v_cmp_ge_f32_e64 s[0:1], 0, v48
	v_and_b32_e32 v43, 0xffff0000, v34
	v_lshlrev_b32_e32 v34, 16, v35
	v_cndmask_b32_e64 v45, v45, v46, s[0:1]
	v_cmp_lt_f32_e64 s[0:1], 0, v49
	v_and_b32_e32 v35, 0xffff0000, v35
	s_nop 0
	v_cndmask_b32_e64 v45, v45, v47, s[0:1]
	v_mul_f32_e32 v46, 0x37800000, v45
	v_cndmask_b32_e32 v45, v45, v46, vcc
	v_cmp_class_f32_e32 vcc, v44, v145
	s_nop 1
	v_cndmask_b32_e32 v44, v45, v44, vcc
	v_div_scale_f32 v45, s[0:1], v44, v44, 1.0
	v_rcp_f32_e32 v46, v45
	v_div_scale_f32 v47, vcc, 1.0, v44, 1.0
	v_fma_f32 v48, -v45, v46, 1.0
	v_fmac_f32_e32 v46, v48, v46
	v_mul_f32_e32 v48, v47, v46
	v_fma_f32 v49, -v45, v48, v47
	v_fmac_f32_e32 v48, v49, v46
	v_fma_f32 v45, -v45, v48, v47
	v_div_fmas_f32 v45, v45, v46, v48
	v_div_fixup_f32 v44, v45, v44, 1.0
	v_pk_mul_f32 v[28:29], v[28:29], v[44:45] op_sel_hi:[1,0]
	v_pk_mul_f32 v[30:31], v[30:31], v[44:45] op_sel_hi:[1,0]
	v_pk_mul_f32 v[46:47], v[24:25], v[44:45] op_sel_hi:[1,0]
	v_pk_mul_f32 v[48:49], v[26:27], v[44:45] op_sel_hi:[1,0]
	v_pk_fma_f32 v[26:27], v[126:127], v[30:31], v[32:33]
	v_pk_fma_f32 v[24:25], v[124:125], v[28:29], v[40:41]
	v_pk_fma_f32 v[30:31], v[122:123], v[48:49], v[34:35]
	v_pk_fma_f32 v[28:29], v[120:121], v[46:47], v[42:43]
	global_store_dwordx4 v[36:37], v[24:27], off nt
	global_store_dwordx4 v[36:37], v[28:31], off offset:16 nt
	global_load_dwordx4 v[24:27], v[38:39], off
	v_pk_mul_f32 v[20:21], v[20:21], v[44:45] op_sel_hi:[1,0]
	v_lshl_add_u64 v[28:29], s[10:11], 0, v[152:153]
	v_lshl_add_u64 v[30:31], v[28:29], 2, s[6:7]
	v_lshlrev_b64 v[28:29], 10, v[28:29]
	v_pk_mul_f32 v[22:23], v[22:23], v[44:45] op_sel_hi:[1,0]
	v_pk_mul_f32 v[38:39], v[16:17], v[44:45] op_sel_hi:[1,0]
	v_pk_mul_f32 v[40:41], v[18:19], v[44:45] op_sel_hi:[1,0]
	v_lshl_add_u64 v[28:29], v[28:29], 0, v[154:155]
	v_lshlrev_b64 v[32:33], 1, v[28:29]
	v_lshl_add_u64 v[34:35], s[4:5], 0, v[32:33]
	v_or_b32_e32 v32, 0x100, v32
	s_waitcnt vmcnt(0)
	v_lshlrev_b32_e32 v16, 16, v24
	v_and_b32_e32 v17, 0xffff0000, v24
	v_lshlrev_b32_e32 v18, 16, v25
	v_and_b32_e32 v19, 0xffff0000, v25
	v_lshlrev_b32_e32 v24, 16, v26
	v_and_b32_e32 v25, 0xffff0000, v26
	v_lshlrev_b32_e32 v26, 16, v27
	v_and_b32_e32 v27, 0xffff0000, v27
	v_pk_fma_f32 v[18:19], v[118:119], v[22:23], v[18:19]
	v_pk_fma_f32 v[16:17], v[116:117], v[20:21], v[16:17]
	v_pk_fma_f32 v[22:23], v[110:111], v[40:41], v[26:27]
	v_pk_fma_f32 v[20:21], v[108:109], v[38:39], v[24:25]
	global_store_dwordx4 v[36:37], v[16:19], off offset:512 nt
	global_store_dwordx4 v[36:37], v[20:23], off offset:528 nt
	global_load_dword v24, v[30:31], off sc1
	s_nop 0
	global_load_dwordx4 v[16:19], v[34:35], off
	v_lshl_add_u64 v[20:21], v[28:29], 2, s[14:15]
	v_lshl_add_u64 v[22:23], s[4:5], 0, v[32:33]
	s_waitcnt vmcnt(1)
	v_fmac_f32_e32 v147, 0x3a800000, v24
	v_mul_f32_e32 v26, 0x4f800000, v147
	v_cmp_gt_f32_e32 vcc, s2, v147
	s_waitcnt vmcnt(0)
	v_lshlrev_b32_e32 v24, 16, v16
	v_and_b32_e32 v25, 0xffff0000, v16
	v_cndmask_b32_e32 v28, v147, v26, vcc
	v_sqrt_f32_e32 v29, v28
	v_lshlrev_b32_e32 v16, 16, v17
	v_and_b32_e32 v17, 0xffff0000, v17
	v_lshlrev_b32_e32 v26, 16, v18
	v_add_u32_e32 v30, -1, v29
	v_add_u32_e32 v31, 1, v29
	v_fma_f32 v32, -v30, v29, v28
	v_fma_f32 v33, -v31, v29, v28
	v_cmp_ge_f32_e64 s[0:1], 0, v32
	v_and_b32_e32 v27, 0xffff0000, v18
	v_lshlrev_b32_e32 v18, 16, v19
	v_cndmask_b32_e64 v29, v29, v30, s[0:1]
	v_cmp_lt_f32_e64 s[0:1], 0, v33
	v_and_b32_e32 v19, 0xffff0000, v19
	s_nop 0
	v_cndmask_b32_e64 v29, v29, v31, s[0:1]
	v_mul_f32_e32 v30, 0x37800000, v29
	v_cndmask_b32_e32 v29, v29, v30, vcc
	v_cmp_class_f32_e32 vcc, v28, v145
	s_nop 1
	v_cndmask_b32_e32 v28, v29, v28, vcc
	v_div_scale_f32 v29, s[0:1], v28, v28, 1.0
	v_rcp_f32_e32 v30, v29
	v_div_scale_f32 v31, vcc, 1.0, v28, 1.0
	v_fma_f32 v32, -v29, v30, 1.0
	v_fmac_f32_e32 v30, v32, v30
	v_mul_f32_e32 v32, v31, v30
	v_fma_f32 v33, -v29, v32, v31
	v_fmac_f32_e32 v32, v33, v30
	v_fma_f32 v29, -v29, v32, v31
	v_div_fmas_f32 v29, v29, v30, v32
	v_div_fixup_f32 v28, v29, v28, 1.0
	v_pk_mul_f32 v[12:13], v[12:13], v[28:29] op_sel_hi:[1,0]
	v_pk_mul_f32 v[14:15], v[14:15], v[28:29] op_sel_hi:[1,0]
	v_pk_mul_f32 v[30:31], v[8:9], v[28:29] op_sel_hi:[1,0]
	v_pk_mul_f32 v[32:33], v[10:11], v[28:29] op_sel_hi:[1,0]
	v_pk_fma_f32 v[10:11], v[126:127], v[14:15], v[16:17]
	v_pk_fma_f32 v[8:9], v[124:125], v[12:13], v[24:25]
	v_pk_fma_f32 v[14:15], v[122:123], v[32:33], v[18:19]
	v_pk_fma_f32 v[12:13], v[120:121], v[30:31], v[26:27]
	global_store_dwordx4 v[20:21], v[8:11], off nt
	global_store_dwordx4 v[20:21], v[12:15], off offset:16 nt
	global_load_dwordx4 v[8:11], v[22:23], off
	v_pk_mul_f32 v[4:5], v[4:5], v[28:29] op_sel_hi:[1,0]
	v_pk_mul_f32 v[6:7], v[6:7], v[28:29] op_sel_hi:[1,0]
	v_pk_mul_f32 v[12:13], v[0:1], v[28:29] op_sel_hi:[1,0]
	v_pk_mul_f32 v[14:15], v[2:3], v[28:29] op_sel_hi:[1,0]
	s_waitcnt vmcnt(0)
	v_lshlrev_b32_e32 v0, 16, v8
	v_and_b32_e32 v1, 0xffff0000, v8
	v_lshlrev_b32_e32 v2, 16, v9
	v_and_b32_e32 v3, 0xffff0000, v9
	v_lshlrev_b32_e32 v8, 16, v10
	v_and_b32_e32 v9, 0xffff0000, v10
	v_lshlrev_b32_e32 v10, 16, v11
	v_and_b32_e32 v11, 0xffff0000, v11
	v_pk_fma_f32 v[2:3], v[118:119], v[6:7], v[2:3]
	v_pk_fma_f32 v[0:1], v[116:117], v[4:5], v[0:1]
	v_pk_fma_f32 v[6:7], v[110:111], v[14:15], v[10:11]
	v_pk_fma_f32 v[4:5], v[108:109], v[12:13], v[8:9]
	global_store_dwordx4 v[20:21], v[0:3], off offset:512 nt
	global_store_dwordx4 v[20:21], v[4:7], off offset:528 nt
	s_barrier

; DI unsigned pk_bf16(float lo, float hi) { f32x2 v = {lo, hi}; bf16x2_t b = __builtin_convertvector(v, bf16x2_t); return __builtin_bit_cast(unsigned, b); }
; DI float bflo(unsigned w) { return __uint_as_float(w << 16); }
; DI float bfhi(unsigned w) { return __uint_as_float(w & 0xffff0000u); }
;     __device__ __forceinline__ void fused(f32x4 (&acc)[2][2][4][2], const pg8::Unit& u, int wr, int wc, int fr, int fq, PG8_LAS unsigned char* lds, int wid, int lane) const {
;     ...
;         const int colb = u.pn * 256 + wc * 32 + 8 * fq;
;         f32x4 gv[2][2];
; #pragma unroll
;         for (int bj = 0; bj < 2; ++bj)
; #pragma unroll
;             for (int n = 0; n < 2; ++n) gv[bj][n] = *(const f32x4*)(gA + colb + bj * 128 + 4 * n);
; #pragma unroll
;         for (int ai = 0; ai < 2; ++ai)
; #pragma unroll
;             for (int m = 0; m < 4; ++m) {
;                 const int rl = ai * 128 + wr * 64 + m * 16 + fr; const size_t row = (size_t)u.pm * 256 + rl;
;                 const float rm = 1.f / sqrtf(__hip_atomic_load(ssqm + row, __ATOMIC_RELAXED, __HIP_MEMORY_SCOPE_AGENT) * (1.f / DM) + RMS_EPS);
;                 float sh = 0.f;
; #pragma unroll
;                 for (int bj = 0; bj < 2; ++bj) {
;                     const size_t off = row * DM + colb + bj * 128;
;                     f32x4 h0, h1;
;                     if (IN16) { const u32x4 hw = *(const u32x4*)((const bf16_t*)hin + off); h0 = (f32x4){bflo(hw.x), bfhi(hw.x), bflo(hw.y), bfhi(hw.y)}; h1 = (f32x4){bflo(hw.z), bfhi(hw.z), bflo(hw.w), bfhi(hw.w)}; }
;                     else { h0 = *(const f32x4*)((const float*)hin + off); h1 = *(const f32x4*)((const float*)hin + off + 4); }
;                     h0 = h0 + acc[ai][bj][m][0] * rm * gv[bj][0]; h1 = h1 + acc[ai][bj][m][1] * rm * gv[bj][1];
;                     sh += ((h0[0] * h0[0] + h0[1] * h0[1]) + (h0[2] * h0[2] + h0[3] * h0[3])) + ((h1[0] * h1[0] + h1[1] * h1[1]) + (h1[2] * h1[2] + h1[3] * h1[3]));
;                     if (OUT16) { u32x4 w; w.x = pk_bf16(h0[0], h0[1]); w.y = pk_bf16(h0[2], h0[3]); w.z = pk_bf16(h1[0], h1[1]); w.w = pk_bf16(h1[2], h1[3]); *(u32x4*)((bf16_t*)hout + off) = w; }
;                     else { *(f32x4*)((float*)hout + off) = h0; *(f32x4*)((float*)hout + off + 4) = h1; }
.LBB0_1666:
	s_or_b64 exec, exec, s[0:1]
	s_lshl_b32 s0, s26, 5
	s_lshl_b32 s1, s22, 8
	s_or_b32 s0, s1, s0
	v_or_b32_e32 v144, s0, v156
	s_lshl_b64 s[2:3], s[2:3], 8
	v_mov_b32_e32 v153, 0
	v_ashrrev_i32_e32 v145, 31, v144
	v_lshl_add_u64 v[146:147], s[2:3], 0, v[152:153]
	v_lshl_add_u64 v[116:117], v[144:145], 2, s[8:9]
	v_lshl_add_u64 v[148:149], v[146:147], 2, s[6:7]
	s_barrier
	global_load_dwordx4 v[120:123], v[116:117], off offset:16
	global_load_dwordx4 v[124:127], v[116:117], off
	global_load_dwordx4 v[112:115], v[116:117], off offset:528
	s_nop 0
	global_load_dwordx4 v[116:119], v[116:117], off offset:512
	v_lshlrev_b64 v[146:147], 10, v[146:147]
	global_load_dword v158, v[148:149], off sc1
	v_lshl_add_u64 v[154:155], v[146:147], 0, v[144:145]
	v_lshlrev_b64 v[156:157], 1, v[154:155]
	v_lshl_add_u64 v[146:147], s[4:5], 0, v[156:157]
	global_load_dwordx4 v[148:151], v[146:147], off
	v_mov_b32_e32 v147, 0x358637bd
	s_mov_b32 s8, 0xf800000
	v_mov_b32_e32 v146, 0x260
	v_readlane_b32 s12, v251, 0
	v_readlane_b32 s14, v251, 2
	v_readlane_b32 s15, v251, 3
	s_mov_b64 s[10:11], s[14:15]
	v_lshl_add_u64 v[154:155], v[154:155], 2, s[10:11]
	v_or_b32_e32 v156, 0x100, v156
	v_lshl_add_u64 v[156:157], s[4:5], 0, v[156:157]
	v_readlane_b32 s13, v251, 1
	s_waitcnt vmcnt(1)
	v_fmamk_f32 v158, v158, 0x3a800000, v147
	v_mul_f32_e32 v159, 0x4f800000, v158
	v_cmp_gt_f32_e32 vcc, s8, v158
	s_waitcnt vmcnt(0)
	v_lshlrev_b32_e32 v160, 16, v150
	v_cndmask_b32_e32 v162, v158, v159, vcc
	v_sqrt_f32_e32 v163, v162
	v_lshlrev_b32_e32 v158, 16, v148
	v_and_b32_e32 v159, 0xffff0000, v148
	v_lshlrev_b32_e32 v148, 16, v149
	v_add_u32_e32 v164, -1, v163
	v_add_u32_e32 v165, 1, v163
	v_fma_f32 v166, -v164, v163, v162
	v_fma_f32 v167, -v165, v163, v162
	v_cmp_ge_f32_e64 s[0:1], 0, v166
	v_and_b32_e32 v149, 0xffff0000, v149
	v_and_b32_e32 v161, 0xffff0000, v150
	v_cndmask_b32_e64 v163, v163, v164, s[0:1]
	v_cmp_lt_f32_e64 s[0:1], 0, v167
	v_lshlrev_b32_e32 v150, 16, v151
	v_and_b32_e32 v151, 0xffff0000, v151
	v_cndmask_b32_e64 v163, v163, v165, s[0:1]
	v_mul_f32_e32 v164, 0x37800000, v163
	v_cndmask_b32_e32 v163, v163, v164, vcc
	v_cmp_class_f32_e32 vcc, v162, v146
	s_nop 1
	v_cndmask_b32_e32 v162, v163, v162, vcc
	v_div_scale_f32 v163, s[0:1], v162, v162, 1.0
	v_rcp_f32_e32 v164, v163
	v_div_scale_f32 v165, vcc, 1.0, v162, 1.0
	v_fma_f32 v166, -v163, v164, 1.0
	v_fmac_f32_e32 v164, v166, v164
	v_mul_f32_e32 v166, v165, v164
	v_fma_f32 v167, -v163, v166, v165
	v_fmac_f32_e32 v166, v167, v164
	v_fma_f32 v163, -v163, v166, v165
	v_div_fmas_f32 v163, v163, v164, v166
	v_div_fixup_f32 v162, v163, v162, 1.0
	v_pk_mul_f32 v[140:141], v[140:141], v[162:163] op_sel_hi:[1,0]
	v_pk_mul_f32 v[142:143], v[142:143], v[162:163] op_sel_hi:[1,0]
	v_pk_mul_f32 v[164:165], v[136:137], v[162:163] op_sel_hi:[1,0]
	v_pk_mul_f32 v[166:167], v[138:139], v[162:163] op_sel_hi:[1,0]
	v_pk_fma_f32 v[138:139], v[126:127], v[142:143], v[148:149]
	v_pk_fma_f32 v[136:137], v[124:125], v[140:141], v[158:159]
	v_pk_fma_f32 v[142:143], v[122:123], v[166:167], v[150:151]
	v_pk_fma_f32 v[140:141], v[120:121], v[164:165], v[160:161]
	global_store_dwordx4 v[154:155], v[136:139], off nt
	global_store_dwordx4 v[154:155], v[140:143], off offset:16 nt
	global_load_dwordx4 v[136:139], v[156:157], off
	v_pk_mul_f32 v[132:133], v[132:133], v[162:163] op_sel_hi:[1,0]
	v_or_b32_e32 v140, 16, v152
	v_mov_b32_e32 v141, v153
	v_lshl_add_u64 v[140:141], s[2:3], 0, v[140:141]
	v_lshl_add_u64 v[142:143], v[140:141], 2, s[6:7]
	v_lshlrev_b64 v[140:141], 10, v[140:141]
	v_pk_mul_f32 v[134:135], v[134:135], v[162:163] op_sel_hi:[1,0]
	v_pk_mul_f32 v[156:157], v[128:129], v[162:163] op_sel_hi:[1,0]
	v_pk_mul_f32 v[158:159], v[130:131], v[162:163] op_sel_hi:[1,0]
	v_lshl_add_u64 v[140:141], v[140:141], 0, v[144:145]
	v_lshlrev_b64 v[148:149], 1, v[140:141]
	v_lshl_add_u64 v[150:151], s[4:5], 0, v[148:149]
	v_or_b32_e32 v148, 0x100, v148
	s_waitcnt vmcnt(0)
	v_lshlrev_b32_e32 v128, 16, v136
	v_and_b32_e32 v129, 0xffff0000, v136
	v_lshlrev_b32_e32 v130, 16, v137
	v_and_b32_e32 v131, 0xffff0000, v137
	v_lshlrev_b32_e32 v136, 16, v138
	v_and_b32_e32 v137, 0xffff0000, v138
	v_lshlrev_b32_e32 v138, 16, v139
	v_and_b32_e32 v139, 0xffff0000, v139
	v_pk_fma_f32 v[130:131], v[118:119], v[134:135], v[130:131]
	v_pk_fma_f32 v[128:129], v[116:117], v[132:133], v[128:129]
	v_pk_fma_f32 v[134:135], v[114:115], v[158:159], v[138:139]
	v_pk_fma_f32 v[132:133], v[112:113], v[156:157], v[136:137]
	global_store_dwordx4 v[154:155], v[128:131], off offset:512 nt
	global_store_dwordx4 v[154:155], v[132:135], off offset:528 nt
	global_load_dword v136, v[142:143], off sc1
	s_nop 0
	global_load_dwordx4 v[128:131], v[150:151], off
	v_lshl_add_u64 v[132:133], v[140:141], 2, s[10:11]
	v_lshl_add_u64 v[134:135], s[4:5], 0, v[148:149]
	s_waitcnt vmcnt(1)
	v_fmamk_f32 v138, v136, 0x3a800000, v147
	v_mul_f32_e32 v139, 0x4f800000, v138
	v_cmp_gt_f32_e32 vcc, s8, v138
	s_waitcnt vmcnt(0)
; DI unsigned pk_bf16(float lo, float hi) { f32x2 v = {lo, hi}; bf16x2_t b = __builtin_convertvector(v, bf16x2_t); return __builtin_bit_cast(unsigned, b); }
; DI float bflo(unsigned w) { return __uint_as_float(w << 16); }
; DI float bfhi(unsigned w) { return __uint_as_float(w & 0xffff0000u); }
;     __device__ __forceinline__ void fused(f32x4 (&acc)[2][2][4][2], const pg8::Unit& u, int wr, int wc, int fr, int fq, PG8_LAS unsigned char* lds, int wid, int lane) const {
;     ...
;                 const int rl = ai * 128 + wr * 64 + m * 16 + fr; const size_t row = (size_t)u.pm * 256 + rl;
;                 const float rm = 1.f / sqrtf(__hip_atomic_load(ssqm + row, __ATOMIC_RELAXED, __HIP_MEMORY_SCOPE_AGENT) * (1.f / DM) + RMS_EPS);
;                 float sh = 0.f;
; #pragma unroll
;                 for (int bj = 0; bj < 2; ++bj) {
;                     const size_t off = row * DM + colb + bj * 128;
;                     f32x4 h0, h1;
;                     if (IN16) { const u32x4 hw = *(const u32x4*)((const bf16_t*)hin + off); h0 = (f32x4){bflo(hw.x), bfhi(hw.x), bflo(hw.y), bfhi(hw.y)}; h1 = (f32x4){bflo(hw.z), bfhi(hw.z), bflo(hw.w), bfhi(hw.w)}; }
;                     else { h0 = *(const f32x4*)((const float*)hin + off); h1 = *(const f32x4*)((const float*)hin + off + 4); }
;                     h0 = h0 + acc[ai][bj][m][0] * rm * gv[bj][0]; h1 = h1 + acc[ai][bj][m][1] * rm * gv[bj][1];
;                     sh += ((h0[0] * h0[0] + h0[1] * h0[1]) + (h0[2] * h0[2] + h0[3] * h0[3])) + ((h1[0] * h1[0] + h1[1] * h1[1]) + (h1[2] * h1[2] + h1[3] * h1[3]));
;                     if (OUT16) { u32x4 w; w.x = pk_bf16(h0[0], h0[1]); w.y = pk_bf16(h0[2], h0[3]); w.z = pk_bf16(h1[0], h1[1]); w.w = pk_bf16(h1[2], h1[3]); *(u32x4*)((bf16_t*)hout + off) = w; }
;                     else { *(f32x4*)((float*)hout + off) = h0; *(f32x4*)((float*)hout + off + 4) = h1; }
	v_lshlrev_b32_e32 v136, 16, v128
	v_and_b32_e32 v137, 0xffff0000, v128
	v_cndmask_b32_e32 v140, v138, v139, vcc
	v_sqrt_f32_e32 v141, v140
	v_lshlrev_b32_e32 v128, 16, v129
	v_and_b32_e32 v129, 0xffff0000, v129
	v_lshlrev_b32_e32 v138, 16, v130
	v_add_u32_e32 v142, -1, v141
	v_add_u32_e32 v143, 1, v141
	v_fma_f32 v148, -v142, v141, v140
	v_fma_f32 v149, -v143, v141, v140
	v_cmp_ge_f32_e64 s[0:1], 0, v148
	v_and_b32_e32 v139, 0xffff0000, v130
	v_lshlrev_b32_e32 v130, 16, v131
	v_cndmask_b32_e64 v141, v141, v142, s[0:1]
	v_cmp_lt_f32_e64 s[0:1], 0, v149
	v_and_b32_e32 v131, 0xffff0000, v131
	s_nop 0
	v_cndmask_b32_e64 v141, v141, v143, s[0:1]
	v_mul_f32_e32 v142, 0x37800000, v141
	v_cndmask_b32_e32 v141, v141, v142, vcc
	v_cmp_class_f32_e32 vcc, v140, v146
	s_nop 1
	v_cndmask_b32_e32 v140, v141, v140, vcc
	v_div_scale_f32 v141, s[0:1], v140, v140, 1.0
	v_rcp_f32_e32 v142, v141
	v_div_scale_f32 v143, vcc, 1.0, v140, 1.0
	v_fma_f32 v148, -v141, v142, 1.0
	v_fmac_f32_e32 v142, v148, v142
	v_mul_f32_e32 v148, v143, v142
	v_fma_f32 v149, -v141, v148, v143
	v_fmac_f32_e32 v148, v149, v142
	v_fma_f32 v141, -v141, v148, v143
	v_div_fmas_f32 v141, v141, v142, v148
	v_div_fixup_f32 v140, v141, v140, 1.0
	v_pk_mul_f32 v[108:109], v[108:109], v[140:141] op_sel_hi:[1,0]
	v_pk_mul_f32 v[110:111], v[110:111], v[140:141] op_sel_hi:[1,0]
	v_pk_mul_f32 v[142:143], v[104:105], v[140:141] op_sel_hi:[1,0]
	v_pk_mul_f32 v[148:149], v[106:107], v[140:141] op_sel_hi:[1,0]
	v_pk_fma_f32 v[106:107], v[126:127], v[110:111], v[128:129]
	v_pk_fma_f32 v[104:105], v[124:125], v[108:109], v[136:137]
	v_pk_fma_f32 v[110:111], v[122:123], v[148:149], v[130:131]
	v_pk_fma_f32 v[108:109], v[120:121], v[142:143], v[138:139]
	global_store_dwordx4 v[132:133], v[104:107], off nt
	global_store_dwordx4 v[132:133], v[108:111], off offset:16 nt
	global_load_dwordx4 v[104:107], v[134:135], off
	v_pk_mul_f32 v[100:101], v[100:101], v[140:141] op_sel_hi:[1,0]
	v_or_b32_e32 v108, 32, v152
	v_mov_b32_e32 v109, v153
	v_lshl_add_u64 v[108:109], s[2:3], 0, v[108:109]
	v_lshl_add_u64 v[110:111], v[108:109], 2, s[6:7]
	v_lshlrev_b64 v[108:109], 10, v[108:109]
	v_pk_mul_f32 v[102:103], v[102:103], v[140:141] op_sel_hi:[1,0]
	v_pk_mul_f32 v[134:135], v[96:97], v[140:141] op_sel_hi:[1,0]
	v_pk_mul_f32 v[136:137], v[98:99], v[140:141] op_sel_hi:[1,0]
	v_lshl_add_u64 v[108:109], v[108:109], 0, v[144:145]
	v_lshlrev_b64 v[128:129], 1, v[108:109]
	v_lshl_add_u64 v[130:131], s[4:5], 0, v[128:129]
	v_or_b32_e32 v128, 0x100, v128
	s_waitcnt vmcnt(0)
	v_lshlrev_b32_e32 v96, 16, v104
	v_and_b32_e32 v97, 0xffff0000, v104
	v_lshlrev_b32_e32 v98, 16, v105
	v_and_b32_e32 v99, 0xffff0000, v105
	v_lshlrev_b32_e32 v104, 16, v106
	v_and_b32_e32 v105, 0xffff0000, v106
	v_lshlrev_b32_e32 v106, 16, v107
	v_and_b32_e32 v107, 0xffff0000, v107
	v_pk_fma_f32 v[98:99], v[118:119], v[102:103], v[98:99]
	v_pk_fma_f32 v[96:97], v[116:117], v[100:101], v[96:97]
	v_pk_fma_f32 v[102:103], v[114:115], v[136:137], v[106:107]
	v_pk_fma_f32 v[100:101], v[112:113], v[134:135], v[104:105]
	global_store_dwordx4 v[132:133], v[96:99], off offset:512 nt
	global_store_dwordx4 v[132:133], v[100:103], off offset:528 nt
	global_load_dword v104, v[110:111], off sc1
	s_nop 0
	global_load_dwordx4 v[96:99], v[130:131], off
	v_lshl_add_u64 v[100:101], v[108:109], 2, s[10:11]
	v_lshl_add_u64 v[102:103], s[4:5], 0, v[128:129]
	s_waitcnt vmcnt(1)
	v_fmamk_f32 v106, v104, 0x3a800000, v147
	v_mul_f32_e32 v107, 0x4f800000, v106
	v_cmp_gt_f32_e32 vcc, s8, v106
	s_waitcnt vmcnt(0)
	v_lshlrev_b32_e32 v104, 16, v96
	v_and_b32_e32 v105, 0xffff0000, v96
	v_cndmask_b32_e32 v108, v106, v107, vcc
	v_sqrt_f32_e32 v109, v108
	v_lshlrev_b32_e32 v96, 16, v97
	v_and_b32_e32 v97, 0xffff0000, v97
	v_lshlrev_b32_e32 v106, 16, v98
	v_add_u32_e32 v110, -1, v109
	v_add_u32_e32 v111, 1, v109
	v_fma_f32 v128, -v110, v109, v108
	v_fma_f32 v129, -v111, v109, v108
	v_cmp_ge_f32_e64 s[0:1], 0, v128
	v_and_b32_e32 v107, 0xffff0000, v98
	v_lshlrev_b32_e32 v98, 16, v99
	v_cndmask_b32_e64 v109, v109, v110, s[0:1]
	v_cmp_lt_f32_e64 s[0:1], 0, v129
	v_and_b32_e32 v99, 0xffff0000, v99
	s_nop 0
	v_cndmask_b32_e64 v109, v109, v111, s[0:1]
	v_mul_f32_e32 v110, 0x37800000, v109
	v_cndmask_b32_e32 v109, v109, v110, vcc
	v_cmp_class_f32_e32 vcc, v108, v146
	s_nop 1
	v_cndmask_b32_e32 v108, v109, v108, vcc
	v_div_scale_f32 v109, s[0:1], v108, v108, 1.0
	v_rcp_f32_e32 v110, v109
	v_div_scale_f32 v111, vcc, 1.0, v108, 1.0
	v_fma_f32 v128, -v109, v110, 1.0
	v_fmac_f32_e32 v110, v128, v110
	v_mul_f32_e32 v128, v111, v110
	v_fma_f32 v129, -v109, v128, v111
	v_fmac_f32_e32 v128, v129, v110
	v_fma_f32 v109, -v109, v128, v111
	v_div_fmas_f32 v109, v109, v110, v128
	v_div_fixup_f32 v108, v109, v108, 1.0
	v_pk_mul_f32 v[92:93], v[92:93], v[108:109] op_sel_hi:[1,0]
	v_pk_mul_f32 v[94:95], v[94:95], v[108:109] op_sel_hi:[1,0]
	v_pk_mul_f32 v[110:111], v[88:89], v[108:109] op_sel_hi:[1,0]
	v_pk_mul_f32 v[128:129], v[90:91], v[108:109] op_sel_hi:[1,0]
	v_pk_fma_f32 v[90:91], v[126:127], v[94:95], v[96:97]
	v_pk_fma_f32 v[88:89], v[124:125], v[92:93], v[104:105]
	v_pk_fma_f32 v[94:95], v[122:123], v[128:129], v[98:99]
	v_pk_fma_f32 v[92:93], v[120:121], v[110:111], v[106:107]
	global_store_dwordx4 v[100:101], v[88:91], off nt
	global_store_dwordx4 v[100:101], v[92:95], off offset:16 nt
	global_load_dwordx4 v[88:91], v[102:103], off
	v_pk_mul_f32 v[84:85], v[84:85], v[108:109] op_sel_hi:[1,0]
	v_or_b32_e32 v92, 48, v152
	v_mov_b32_e32 v93, v153
	v_lshl_add_u64 v[92:93], s[2:3], 0, v[92:93]
	v_lshl_add_u64 v[94:95], v[92:93], 2, s[6:7]
	v_lshlrev_b64 v[92:93], 10, v[92:93]
	v_pk_mul_f32 v[86:87], v[86:87], v[108:109] op_sel_hi:[1,0]
	v_pk_mul_f32 v[102:103], v[80:81], v[108:109] op_sel_hi:[1,0]
	v_pk_mul_f32 v[104:105], v[82:83], v[108:109] op_sel_hi:[1,0]
	v_lshl_add_u64 v[92:93], v[92:93], 0, v[144:145]
	v_lshlrev_b64 v[96:97], 1, v[92:93]
	v_lshl_add_u64 v[98:99], s[4:5], 0, v[96:97]
	v_or_b32_e32 v96, 0x100, v96
	s_waitcnt vmcnt(0)
; DI unsigned pk_bf16(float lo, float hi) { f32x2 v = {lo, hi}; bf16x2_t b = __builtin_convertvector(v, bf16x2_t); return __builtin_bit_cast(unsigned, b); }
; DI float bflo(unsigned w) { return __uint_as_float(w << 16); }
; DI float bfhi(unsigned w) { return __uint_as_float(w & 0xffff0000u); }
;     __device__ __forceinline__ void fused(f32x4 (&acc)[2][2][4][2], const pg8::Unit& u, int wr, int wc, int fr, int fq, PG8_LAS unsigned char* lds, int wid, int lane) const {
;     ...
;                 const int rl = ai * 128 + wr * 64 + m * 16 + fr; const size_t row = (size_t)u.pm * 256 + rl;
;                 const float rm = 1.f / sqrtf(__hip_atomic_load(ssqm + row, __ATOMIC_RELAXED, __HIP_MEMORY_SCOPE_AGENT) * (1.f / DM) + RMS_EPS);
;                 float sh = 0.f;
; #pragma unroll
;                 for (int bj = 0; bj < 2; ++bj) {
;                     const size_t off = row * DM + colb + bj * 128;
;                     f32x4 h0, h1;
;                     if (IN16) { const u32x4 hw = *(const u32x4*)((const bf16_t*)hin + off); h0 = (f32x4){bflo(hw.x), bfhi(hw.x), bflo(hw.y), bfhi(hw.y)}; h1 = (f32x4){bflo(hw.z), bfhi(hw.z), bflo(hw.w), bfhi(hw.w)}; }
;                     else { h0 = *(const f32x4*)((const float*)hin + off); h1 = *(const f32x4*)((const float*)hin + off + 4); }
;                     h0 = h0 + acc[ai][bj][m][0] * rm * gv[bj][0]; h1 = h1 + acc[ai][bj][m][1] * rm * gv[bj][1];
;                     sh += ((h0[0] * h0[0] + h0[1] * h0[1]) + (h0[2] * h0[2] + h0[3] * h0[3])) + ((h1[0] * h1[0] + h1[1] * h1[1]) + (h1[2] * h1[2] + h1[3] * h1[3]));
;                     if (OUT16) { u32x4 w; w.x = pk_bf16(h0[0], h0[1]); w.y = pk_bf16(h0[2], h0[3]); w.z = pk_bf16(h1[0], h1[1]); w.w = pk_bf16(h1[2], h1[3]); *(u32x4*)((bf16_t*)hout + off) = w; }
;                     else { *(f32x4*)((float*)hout + off) = h0; *(f32x4*)((float*)hout + off + 4) = h1; }
	v_lshlrev_b32_e32 v80, 16, v88
	v_and_b32_e32 v81, 0xffff0000, v88
	v_lshlrev_b32_e32 v82, 16, v89
	v_and_b32_e32 v83, 0xffff0000, v89
	v_lshlrev_b32_e32 v88, 16, v90
	v_and_b32_e32 v89, 0xffff0000, v90
	v_lshlrev_b32_e32 v90, 16, v91
	v_and_b32_e32 v91, 0xffff0000, v91
	v_pk_fma_f32 v[82:83], v[118:119], v[86:87], v[82:83]
	v_pk_fma_f32 v[80:81], v[116:117], v[84:85], v[80:81]
	v_pk_fma_f32 v[86:87], v[114:115], v[104:105], v[90:91]
	v_pk_fma_f32 v[84:85], v[112:113], v[102:103], v[88:89]
	global_store_dwordx4 v[100:101], v[80:83], off offset:512 nt
	global_store_dwordx4 v[100:101], v[84:87], off offset:528 nt
	global_load_dword v88, v[94:95], off sc1
	s_nop 0
	global_load_dwordx4 v[80:83], v[98:99], off
	v_lshl_add_u64 v[84:85], v[92:93], 2, s[10:11]
	v_lshl_add_u64 v[86:87], s[4:5], 0, v[96:97]
	s_waitcnt vmcnt(1)
	v_fmamk_f32 v90, v88, 0x3a800000, v147
	v_mul_f32_e32 v91, 0x4f800000, v90
	v_cmp_gt_f32_e32 vcc, s8, v90
	s_waitcnt vmcnt(0)
	v_lshlrev_b32_e32 v88, 16, v80
	v_and_b32_e32 v89, 0xffff0000, v80
	v_cndmask_b32_e32 v92, v90, v91, vcc
	v_sqrt_f32_e32 v93, v92
	v_lshlrev_b32_e32 v80, 16, v81
	v_and_b32_e32 v81, 0xffff0000, v81
	v_lshlrev_b32_e32 v90, 16, v82
	v_add_u32_e32 v94, -1, v93
	v_add_u32_e32 v95, 1, v93
	v_fma_f32 v96, -v94, v93, v92
	v_fma_f32 v97, -v95, v93, v92
	v_cmp_ge_f32_e64 s[0:1], 0, v96
	v_and_b32_e32 v91, 0xffff0000, v82
	v_lshlrev_b32_e32 v82, 16, v83
	v_cndmask_b32_e64 v93, v93, v94, s[0:1]
	v_cmp_lt_f32_e64 s[0:1], 0, v97
	v_and_b32_e32 v83, 0xffff0000, v83
	s_nop 0
	v_cndmask_b32_e64 v93, v93, v95, s[0:1]
	v_mul_f32_e32 v94, 0x37800000, v93
	v_cndmask_b32_e32 v93, v93, v94, vcc
	v_cmp_class_f32_e32 vcc, v92, v146
	s_nop 1
	v_cndmask_b32_e32 v92, v93, v92, vcc
	v_div_scale_f32 v93, s[0:1], v92, v92, 1.0
	v_rcp_f32_e32 v94, v93
	v_div_scale_f32 v95, vcc, 1.0, v92, 1.0
	v_fma_f32 v96, -v93, v94, 1.0
	v_fmac_f32_e32 v94, v96, v94
	v_mul_f32_e32 v96, v95, v94
	v_fma_f32 v97, -v93, v96, v95
	v_fmac_f32_e32 v96, v97, v94
	v_fma_f32 v93, -v93, v96, v95
	v_div_fmas_f32 v93, v93, v94, v96
	v_div_fixup_f32 v92, v93, v92, 1.0
	v_pk_mul_f32 v[76:77], v[76:77], v[92:93] op_sel_hi:[1,0]
	v_pk_mul_f32 v[78:79], v[78:79], v[92:93] op_sel_hi:[1,0]
	v_pk_mul_f32 v[94:95], v[72:73], v[92:93] op_sel_hi:[1,0]
	v_pk_mul_f32 v[96:97], v[74:75], v[92:93] op_sel_hi:[1,0]
	v_pk_fma_f32 v[74:75], v[126:127], v[78:79], v[80:81]
	v_pk_fma_f32 v[72:73], v[124:125], v[76:77], v[88:89]
	v_pk_fma_f32 v[78:79], v[122:123], v[96:97], v[82:83]
	v_pk_fma_f32 v[76:77], v[120:121], v[94:95], v[90:91]
	global_store_dwordx4 v[84:85], v[72:75], off nt
	global_store_dwordx4 v[84:85], v[76:79], off offset:16 nt
	global_load_dwordx4 v[72:75], v[86:87], off
	v_pk_mul_f32 v[68:69], v[68:69], v[92:93] op_sel_hi:[1,0]
	v_add_u32_e32 v76, 0x80, v152
	v_mov_b32_e32 v77, v153
	v_lshl_add_u64 v[76:77], s[2:3], 0, v[76:77]
	v_lshl_add_u64 v[78:79], v[76:77], 2, s[6:7]
	v_lshlrev_b64 v[76:77], 10, v[76:77]
	v_pk_mul_f32 v[70:71], v[70:71], v[92:93] op_sel_hi:[1,0]
	v_pk_mul_f32 v[86:87], v[64:65], v[92:93] op_sel_hi:[1,0]
	v_pk_mul_f32 v[88:89], v[66:67], v[92:93] op_sel_hi:[1,0]
	v_lshl_add_u64 v[76:77], v[76:77], 0, v[144:145]
	v_lshlrev_b64 v[80:81], 1, v[76:77]
	v_lshl_add_u64 v[82:83], s[4:5], 0, v[80:81]
	v_or_b32_e32 v80, 0x100, v80
	s_waitcnt vmcnt(0)
	v_lshlrev_b32_e32 v64, 16, v72
	v_and_b32_e32 v65, 0xffff0000, v72
	v_lshlrev_b32_e32 v66, 16, v73
	v_and_b32_e32 v67, 0xffff0000, v73
	v_lshlrev_b32_e32 v72, 16, v74
	v_and_b32_e32 v73, 0xffff0000, v74
	v_lshlrev_b32_e32 v74, 16, v75
	v_and_b32_e32 v75, 0xffff0000, v75
	v_pk_fma_f32 v[66:67], v[118:119], v[70:71], v[66:67]
	v_pk_fma_f32 v[64:65], v[116:117], v[68:69], v[64:65]
	v_pk_fma_f32 v[70:71], v[114:115], v[88:89], v[74:75]
	v_pk_fma_f32 v[68:69], v[112:113], v[86:87], v[72:73]
	global_store_dwordx4 v[84:85], v[64:67], off offset:512 nt
	global_store_dwordx4 v[84:85], v[68:71], off offset:528 nt
	global_load_dword v72, v[78:79], off sc1
	s_nop 0
	global_load_dwordx4 v[64:67], v[82:83], off
	v_lshl_add_u64 v[68:69], v[76:77], 2, s[10:11]
	v_lshl_add_u64 v[70:71], s[4:5], 0, v[80:81]
	s_waitcnt vmcnt(1)
	v_fmamk_f32 v74, v72, 0x3a800000, v147
	v_mul_f32_e32 v75, 0x4f800000, v74
	v_cmp_gt_f32_e32 vcc, s8, v74
	s_waitcnt vmcnt(0)
	v_lshlrev_b32_e32 v72, 16, v64
	v_and_b32_e32 v73, 0xffff0000, v64
	v_cndmask_b32_e32 v76, v74, v75, vcc
	v_sqrt_f32_e32 v77, v76
	v_lshlrev_b32_e32 v64, 16, v65
	v_and_b32_e32 v65, 0xffff0000, v65
	v_lshlrev_b32_e32 v74, 16, v66
	v_add_u32_e32 v78, -1, v77
	v_add_u32_e32 v79, 1, v77
	v_fma_f32 v80, -v78, v77, v76
	v_fma_f32 v81, -v79, v77, v76
	v_cmp_ge_f32_e64 s[0:1], 0, v80
	v_and_b32_e32 v75, 0xffff0000, v66
	v_lshlrev_b32_e32 v66, 16, v67
	v_cndmask_b32_e64 v77, v77, v78, s[0:1]
	v_cmp_lt_f32_e64 s[0:1], 0, v81
	v_and_b32_e32 v67, 0xffff0000, v67
	s_nop 0
	v_cndmask_b32_e64 v77, v77, v79, s[0:1]
	v_mul_f32_e32 v78, 0x37800000, v77
	v_cndmask_b32_e32 v77, v77, v78, vcc
	v_cmp_class_f32_e32 vcc, v76, v146
	s_nop 1
	v_cndmask_b32_e32 v76, v77, v76, vcc
	v_div_scale_f32 v77, s[0:1], v76, v76, 1.0
	v_rcp_f32_e32 v78, v77
	v_div_scale_f32 v79, vcc, 1.0, v76, 1.0
	v_fma_f32 v80, -v77, v78, 1.0
	v_fmac_f32_e32 v78, v80, v78
	v_mul_f32_e32 v80, v79, v78
	v_fma_f32 v81, -v77, v80, v79
	v_fmac_f32_e32 v80, v81, v78
	v_fma_f32 v77, -v77, v80, v79
	v_div_fmas_f32 v77, v77, v78, v80
	v_div_fixup_f32 v76, v77, v76, 1.0
	v_pk_mul_f32 v[60:61], v[60:61], v[76:77] op_sel_hi:[1,0]
	v_pk_mul_f32 v[62:63], v[62:63], v[76:77] op_sel_hi:[1,0]
	v_pk_mul_f32 v[78:79], v[56:57], v[76:77] op_sel_hi:[1,0]
	v_pk_mul_f32 v[80:81], v[58:59], v[76:77] op_sel_hi:[1,0]
	v_pk_fma_f32 v[58:59], v[126:127], v[62:63], v[64:65]
	v_pk_fma_f32 v[56:57], v[124:125], v[60:61], v[72:73]
	v_pk_fma_f32 v[62:63], v[122:123], v[80:81], v[66:67]
	v_pk_fma_f32 v[60:61], v[120:121], v[78:79], v[74:75]
	global_store_dwordx4 v[68:69], v[56:59], off nt
	global_store_dwordx4 v[68:69], v[60:63], off offset:16 nt
	global_load_dwordx4 v[56:59], v[70:71], off
	v_pk_mul_f32 v[52:53], v[52:53], v[76:77] op_sel_hi:[1,0]
	v_add_u32_e32 v60, 0x90, v152
	v_mov_b32_e32 v61, v153
	v_lshl_add_u64 v[60:61], s[2:3], 0, v[60:61]
	v_lshl_add_u64 v[62:63], v[60:61], 2, s[6:7]
	v_lshlrev_b64 v[60:61], 10, v[60:61]
	v_pk_mul_f32 v[54:55], v[54:55], v[76:77] op_sel_hi:[1,0]
	v_pk_mul_f32 v[70:71], v[48:49], v[76:77] op_sel_hi:[1,0]
	v_pk_mul_f32 v[72:73], v[50:51], v[76:77] op_sel_hi:[1,0]
	v_lshl_add_u64 v[60:61], v[60:61], 0, v[144:145]
	v_lshlrev_b64 v[64:65], 1, v[60:61]
	v_lshl_add_u64 v[66:67], s[4:5], 0, v[64:65]
	v_or_b32_e32 v64, 0x100, v64
	s_waitcnt vmcnt(0)
; DI unsigned pk_bf16(float lo, float hi) { f32x2 v = {lo, hi}; bf16x2_t b = __builtin_convertvector(v, bf16x2_t); return __builtin_bit_cast(unsigned, b); }
; DI float bflo(unsigned w) { return __uint_as_float(w << 16); }
; DI float bfhi(unsigned w) { return __uint_as_float(w & 0xffff0000u); }
;     __device__ __forceinline__ void fused(f32x4 (&acc)[2][2][4][2], const pg8::Unit& u, int wr, int wc, int fr, int fq, PG8_LAS unsigned char* lds, int wid, int lane) const {
;     ...
;                 const int rl = ai * 128 + wr * 64 + m * 16 + fr; const size_t row = (size_t)u.pm * 256 + rl;
;                 const float rm = 1.f / sqrtf(__hip_atomic_load(ssqm + row, __ATOMIC_RELAXED, __HIP_MEMORY_SCOPE_AGENT) * (1.f / DM) + RMS_EPS);
;                 float sh = 0.f;
; #pragma unroll
;                 for (int bj = 0; bj < 2; ++bj) {
;                     const size_t off = row * DM + colb + bj * 128;
;                     f32x4 h0, h1;
;                     if (IN16) { const u32x4 hw = *(const u32x4*)((const bf16_t*)hin + off); h0 = (f32x4){bflo(hw.x), bfhi(hw.x), bflo(hw.y), bfhi(hw.y)}; h1 = (f32x4){bflo(hw.z), bfhi(hw.z), bflo(hw.w), bfhi(hw.w)}; }
;                     else { h0 = *(const f32x4*)((const float*)hin + off); h1 = *(const f32x4*)((const float*)hin + off + 4); }
;                     h0 = h0 + acc[ai][bj][m][0] * rm * gv[bj][0]; h1 = h1 + acc[ai][bj][m][1] * rm * gv[bj][1];
;                     sh += ((h0[0] * h0[0] + h0[1] * h0[1]) + (h0[2] * h0[2] + h0[3] * h0[3])) + ((h1[0] * h1[0] + h1[1] * h1[1]) + (h1[2] * h1[2] + h1[3] * h1[3]));
;                     if (OUT16) { u32x4 w; w.x = pk_bf16(h0[0], h0[1]); w.y = pk_bf16(h0[2], h0[3]); w.z = pk_bf16(h1[0], h1[1]); w.w = pk_bf16(h1[2], h1[3]); *(u32x4*)((bf16_t*)hout + off) = w; }
;                     else { *(f32x4*)((float*)hout + off) = h0; *(f32x4*)((float*)hout + off + 4) = h1; }
	v_lshlrev_b32_e32 v48, 16, v56
	v_and_b32_e32 v49, 0xffff0000, v56
	v_lshlrev_b32_e32 v50, 16, v57
	v_and_b32_e32 v51, 0xffff0000, v57
	v_lshlrev_b32_e32 v56, 16, v58
	v_and_b32_e32 v57, 0xffff0000, v58
	v_lshlrev_b32_e32 v58, 16, v59
	v_and_b32_e32 v59, 0xffff0000, v59
	v_pk_fma_f32 v[50:51], v[118:119], v[54:55], v[50:51]
	v_pk_fma_f32 v[48:49], v[116:117], v[52:53], v[48:49]
	v_pk_fma_f32 v[54:55], v[114:115], v[72:73], v[58:59]
	v_pk_fma_f32 v[52:53], v[112:113], v[70:71], v[56:57]
	global_store_dwordx4 v[68:69], v[48:51], off offset:512 nt
	global_store_dwordx4 v[68:69], v[52:55], off offset:528 nt
	global_load_dword v56, v[62:63], off sc1
	s_nop 0
	global_load_dwordx4 v[48:51], v[66:67], off
	v_lshl_add_u64 v[52:53], v[60:61], 2, s[10:11]
	v_lshl_add_u64 v[54:55], s[4:5], 0, v[64:65]
	s_waitcnt vmcnt(1)
	v_fmamk_f32 v58, v56, 0x3a800000, v147
	v_mul_f32_e32 v59, 0x4f800000, v58
	v_cmp_gt_f32_e32 vcc, s8, v58
	s_waitcnt vmcnt(0)
	v_lshlrev_b32_e32 v56, 16, v48
	v_and_b32_e32 v57, 0xffff0000, v48
	v_cndmask_b32_e32 v60, v58, v59, vcc
	v_sqrt_f32_e32 v61, v60
	v_lshlrev_b32_e32 v48, 16, v49
	v_and_b32_e32 v49, 0xffff0000, v49
	v_lshlrev_b32_e32 v58, 16, v50
	v_add_u32_e32 v62, -1, v61
	v_add_u32_e32 v63, 1, v61
	v_fma_f32 v64, -v62, v61, v60
	v_fma_f32 v65, -v63, v61, v60
	v_cmp_ge_f32_e64 s[0:1], 0, v64
	v_and_b32_e32 v59, 0xffff0000, v50
	v_lshlrev_b32_e32 v50, 16, v51
	v_cndmask_b32_e64 v61, v61, v62, s[0:1]
	v_cmp_lt_f32_e64 s[0:1], 0, v65
	v_and_b32_e32 v51, 0xffff0000, v51
	s_nop 0
	v_cndmask_b32_e64 v61, v61, v63, s[0:1]
	v_mul_f32_e32 v62, 0x37800000, v61
	v_cndmask_b32_e32 v61, v61, v62, vcc
	v_cmp_class_f32_e32 vcc, v60, v146
	s_nop 1
	v_cndmask_b32_e32 v60, v61, v60, vcc
	v_div_scale_f32 v61, s[0:1], v60, v60, 1.0
	v_rcp_f32_e32 v62, v61
	v_div_scale_f32 v63, vcc, 1.0, v60, 1.0
	v_fma_f32 v64, -v61, v62, 1.0
	v_fmac_f32_e32 v62, v64, v62
	v_mul_f32_e32 v64, v63, v62
	v_fma_f32 v65, -v61, v64, v63
	v_fmac_f32_e32 v64, v65, v62
	v_fma_f32 v61, -v61, v64, v63
	v_div_fmas_f32 v61, v61, v62, v64
	v_div_fixup_f32 v60, v61, v60, 1.0
	v_pk_mul_f32 v[44:45], v[44:45], v[60:61] op_sel_hi:[1,0]
	v_pk_mul_f32 v[46:47], v[46:47], v[60:61] op_sel_hi:[1,0]
	v_pk_mul_f32 v[62:63], v[40:41], v[60:61] op_sel_hi:[1,0]
	v_pk_mul_f32 v[64:65], v[42:43], v[60:61] op_sel_hi:[1,0]
	v_pk_fma_f32 v[42:43], v[126:127], v[46:47], v[48:49]
	v_pk_fma_f32 v[40:41], v[124:125], v[44:45], v[56:57]
	v_pk_fma_f32 v[46:47], v[122:123], v[64:65], v[50:51]
	v_pk_fma_f32 v[44:45], v[120:121], v[62:63], v[58:59]
	global_store_dwordx4 v[52:53], v[40:43], off nt
	global_store_dwordx4 v[52:53], v[44:47], off offset:16 nt
	global_load_dwordx4 v[40:43], v[54:55], off
	v_pk_mul_f32 v[36:37], v[36:37], v[60:61] op_sel_hi:[1,0]
	v_add_u32_e32 v44, 0xa0, v152
	v_mov_b32_e32 v45, v153
	v_lshl_add_u64 v[44:45], s[2:3], 0, v[44:45]
	v_lshl_add_u64 v[46:47], v[44:45], 2, s[6:7]
	v_lshlrev_b64 v[44:45], 10, v[44:45]
	v_pk_mul_f32 v[38:39], v[38:39], v[60:61] op_sel_hi:[1,0]
	v_pk_mul_f32 v[54:55], v[32:33], v[60:61] op_sel_hi:[1,0]
	v_pk_mul_f32 v[56:57], v[34:35], v[60:61] op_sel_hi:[1,0]
	v_lshl_add_u64 v[44:45], v[44:45], 0, v[144:145]
	v_lshlrev_b64 v[48:49], 1, v[44:45]
	v_lshl_add_u64 v[50:51], s[4:5], 0, v[48:49]
	v_or_b32_e32 v48, 0x100, v48
	v_add_u32_e32 v152, 0xb0, v152
	s_waitcnt vmcnt(0)
	v_lshlrev_b32_e32 v32, 16, v40
	v_and_b32_e32 v33, 0xffff0000, v40
	v_lshlrev_b32_e32 v34, 16, v41
	v_and_b32_e32 v35, 0xffff0000, v41
	v_lshlrev_b32_e32 v40, 16, v42
	v_and_b32_e32 v41, 0xffff0000, v42
	v_lshlrev_b32_e32 v42, 16, v43
	v_and_b32_e32 v43, 0xffff0000, v43
	v_pk_fma_f32 v[34:35], v[118:119], v[38:39], v[34:35]
	v_pk_fma_f32 v[32:33], v[116:117], v[36:37], v[32:33]
	v_pk_fma_f32 v[38:39], v[114:115], v[56:57], v[42:43]
	v_pk_fma_f32 v[36:37], v[112:113], v[54:55], v[40:41]
	global_store_dwordx4 v[52:53], v[32:35], off offset:512 nt
	global_store_dwordx4 v[52:53], v[36:39], off offset:528 nt
	global_load_dword v40, v[46:47], off sc1
	s_nop 0
	global_load_dwordx4 v[32:35], v[50:51], off
	v_lshl_add_u64 v[36:37], v[44:45], 2, s[10:11]
	v_lshl_add_u64 v[38:39], s[4:5], 0, v[48:49]
	s_waitcnt vmcnt(1)
	v_fmamk_f32 v42, v40, 0x3a800000, v147
	v_mul_f32_e32 v43, 0x4f800000, v42
	v_cmp_gt_f32_e32 vcc, s8, v42
	s_waitcnt vmcnt(0)
; DI unsigned pk_bf16(float lo, float hi) { f32x2 v = {lo, hi}; bf16x2_t b = __builtin_convertvector(v, bf16x2_t); return __builtin_bit_cast(unsigned, b); }
; DI float bflo(unsigned w) { return __uint_as_float(w << 16); }
; DI float bfhi(unsigned w) { return __uint_as_float(w & 0xffff0000u); }
;     __device__ __forceinline__ void fused(f32x4 (&acc)[2][2][4][2], const pg8::Unit& u, int wr, int wc, int fr, int fq, PG8_LAS unsigned char* lds, int wid, int lane) const {
;     ...
;                 const int rl = ai * 128 + wr * 64 + m * 16 + fr; const size_t row = (size_t)u.pm * 256 + rl;
;                 const float rm = 1.f / sqrtf(__hip_atomic_load(ssqm + row, __ATOMIC_RELAXED, __HIP_MEMORY_SCOPE_AGENT) * (1.f / DM) + RMS_EPS);
;                 float sh = 0.f;
; #pragma unroll
;                 for (int bj = 0; bj < 2; ++bj) {
;                     const size_t off = row * DM + colb + bj * 128;
;                     f32x4 h0, h1;
;                     if (IN16) { const u32x4 hw = *(const u32x4*)((const bf16_t*)hin + off); h0 = (f32x4){bflo(hw.x), bfhi(hw.x), bflo(hw.y), bfhi(hw.y)}; h1 = (f32x4){bflo(hw.z), bfhi(hw.z), bflo(hw.w), bfhi(hw.w)}; }
;                     else { h0 = *(const f32x4*)((const float*)hin + off); h1 = *(const f32x4*)((const float*)hin + off + 4); }
;                     h0 = h0 + acc[ai][bj][m][0] * rm * gv[bj][0]; h1 = h1 + acc[ai][bj][m][1] * rm * gv[bj][1];
;                     sh += ((h0[0] * h0[0] + h0[1] * h0[1]) + (h0[2] * h0[2] + h0[3] * h0[3])) + ((h1[0] * h1[0] + h1[1] * h1[1]) + (h1[2] * h1[2] + h1[3] * h1[3]));
;                     if (OUT16) { u32x4 w; w.x = pk_bf16(h0[0], h0[1]); w.y = pk_bf16(h0[2], h0[3]); w.z = pk_bf16(h1[0], h1[1]); w.w = pk_bf16(h1[2], h1[3]); *(u32x4*)((bf16_t*)hout + off) = w; }
;                     else { *(f32x4*)((float*)hout + off) = h0; *(f32x4*)((float*)hout + off + 4) = h1; }
	v_lshlrev_b32_e32 v40, 16, v32
	v_and_b32_e32 v41, 0xffff0000, v32
	v_cndmask_b32_e32 v44, v42, v43, vcc
	v_sqrt_f32_e32 v45, v44
	v_lshlrev_b32_e32 v32, 16, v33
	v_and_b32_e32 v33, 0xffff0000, v33
	v_lshlrev_b32_e32 v42, 16, v34
	v_add_u32_e32 v46, -1, v45
	v_add_u32_e32 v47, 1, v45
	v_fma_f32 v48, -v46, v45, v44
	v_fma_f32 v49, -v47, v45, v44
	v_cmp_ge_f32_e64 s[0:1], 0, v48
	v_and_b32_e32 v43, 0xffff0000, v34
	v_lshlrev_b32_e32 v34, 16, v35
	v_cndmask_b32_e64 v45, v45, v46, s[0:1]
	v_cmp_lt_f32_e64 s[0:1], 0, v49
	v_and_b32_e32 v35, 0xffff0000, v35
	s_nop 0
	v_cndmask_b32_e64 v45, v45, v47, s[0:1]
	v_mul_f32_e32 v46, 0x37800000, v45
	v_cndmask_b32_e32 v45, v45, v46, vcc
	v_cmp_class_f32_e32 vcc, v44, v146
	s_nop 1
	v_cndmask_b32_e32 v44, v45, v44, vcc
	v_div_scale_f32 v45, s[0:1], v44, v44, 1.0
	v_rcp_f32_e32 v46, v45
	v_div_scale_f32 v47, vcc, 1.0, v44, 1.0
	v_fma_f32 v48, -v45, v46, 1.0
	v_fmac_f32_e32 v46, v48, v46
	v_mul_f32_e32 v48, v47, v46
	v_fma_f32 v49, -v45, v48, v47
	v_fmac_f32_e32 v48, v49, v46
	v_fma_f32 v45, -v45, v48, v47
	v_div_fmas_f32 v45, v45, v46, v48
	v_div_fixup_f32 v44, v45, v44, 1.0
	v_pk_mul_f32 v[28:29], v[28:29], v[44:45] op_sel_hi:[1,0]
	v_pk_mul_f32 v[30:31], v[30:31], v[44:45] op_sel_hi:[1,0]
	v_pk_mul_f32 v[46:47], v[24:25], v[44:45] op_sel_hi:[1,0]
	v_pk_mul_f32 v[48:49], v[26:27], v[44:45] op_sel_hi:[1,0]
	v_pk_fma_f32 v[26:27], v[126:127], v[30:31], v[32:33]
	v_pk_fma_f32 v[24:25], v[124:125], v[28:29], v[40:41]
	v_pk_fma_f32 v[30:31], v[122:123], v[48:49], v[34:35]
	v_pk_fma_f32 v[28:29], v[120:121], v[46:47], v[42:43]
	global_store_dwordx4 v[36:37], v[24:27], off nt
	global_store_dwordx4 v[36:37], v[28:31], off offset:16 nt
	global_load_dwordx4 v[24:27], v[38:39], off
	v_pk_mul_f32 v[20:21], v[20:21], v[44:45] op_sel_hi:[1,0]
	v_lshl_add_u64 v[28:29], s[2:3], 0, v[152:153]
	v_lshl_add_u64 v[30:31], v[28:29], 2, s[6:7]
	v_lshlrev_b64 v[28:29], 10, v[28:29]
	v_pk_mul_f32 v[22:23], v[22:23], v[44:45] op_sel_hi:[1,0]
	v_pk_mul_f32 v[38:39], v[16:17], v[44:45] op_sel_hi:[1,0]
	v_pk_mul_f32 v[40:41], v[18:19], v[44:45] op_sel_hi:[1,0]
	v_lshl_add_u64 v[28:29], v[28:29], 0, v[144:145]
	v_lshlrev_b64 v[32:33], 1, v[28:29]
	v_lshl_add_u64 v[34:35], s[4:5], 0, v[32:33]
	v_or_b32_e32 v32, 0x100, v32
	s_waitcnt vmcnt(0)
	v_lshlrev_b32_e32 v16, 16, v24
	v_and_b32_e32 v17, 0xffff0000, v24
	v_lshlrev_b32_e32 v18, 16, v25
	v_and_b32_e32 v19, 0xffff0000, v25
	v_lshlrev_b32_e32 v24, 16, v26
	v_and_b32_e32 v25, 0xffff0000, v26
	v_lshlrev_b32_e32 v26, 16, v27
	v_and_b32_e32 v27, 0xffff0000, v27
	v_pk_fma_f32 v[18:19], v[118:119], v[22:23], v[18:19]
	v_pk_fma_f32 v[16:17], v[116:117], v[20:21], v[16:17]
	v_pk_fma_f32 v[22:23], v[114:115], v[40:41], v[26:27]
	v_pk_fma_f32 v[20:21], v[112:113], v[38:39], v[24:25]
	global_store_dwordx4 v[36:37], v[16:19], off offset:512 nt
	global_store_dwordx4 v[36:37], v[20:23], off offset:528 nt
	global_load_dword v24, v[30:31], off sc1
	s_nop 0
	global_load_dwordx4 v[16:19], v[34:35], off
	v_lshl_add_u64 v[20:21], v[28:29], 2, s[10:11]
	v_lshl_add_u64 v[22:23], s[4:5], 0, v[32:33]
	s_waitcnt vmcnt(1)
	v_fmac_f32_e32 v147, 0x3a800000, v24
	v_mul_f32_e32 v26, 0x4f800000, v147
	v_cmp_gt_f32_e32 vcc, s8, v147
	s_waitcnt vmcnt(0)
	v_lshlrev_b32_e32 v24, 16, v16
	v_and_b32_e32 v25, 0xffff0000, v16
	v_cndmask_b32_e32 v28, v147, v26, vcc
	v_sqrt_f32_e32 v29, v28
	v_lshlrev_b32_e32 v16, 16, v17
	v_and_b32_e32 v17, 0xffff0000, v17
	v_lshlrev_b32_e32 v26, 16, v18
	v_add_u32_e32 v30, -1, v29
	v_add_u32_e32 v31, 1, v29
	v_fma_f32 v32, -v30, v29, v28
	v_fma_f32 v33, -v31, v29, v28
	v_cmp_ge_f32_e64 s[0:1], 0, v32
	v_and_b32_e32 v27, 0xffff0000, v18
	v_lshlrev_b32_e32 v18, 16, v19
	v_cndmask_b32_e64 v29, v29, v30, s[0:1]
	v_cmp_lt_f32_e64 s[0:1], 0, v33
	v_and_b32_e32 v19, 0xffff0000, v19
	s_nop 0
	v_cndmask_b32_e64 v29, v29, v31, s[0:1]
	v_mul_f32_e32 v30, 0x37800000, v29
	v_cndmask_b32_e32 v29, v29, v30, vcc
	v_cmp_class_f32_e32 vcc, v28, v146
	s_nop 1
	v_cndmask_b32_e32 v28, v29, v28, vcc
	v_div_scale_f32 v29, s[0:1], v28, v28, 1.0
	v_rcp_f32_e32 v30, v29
	v_div_scale_f32 v31, vcc, 1.0, v28, 1.0
	v_fma_f32 v32, -v29, v30, 1.0
	v_fmac_f32_e32 v30, v32, v30
	v_mul_f32_e32 v32, v31, v30
	v_fma_f32 v33, -v29, v32, v31
	v_fmac_f32_e32 v32, v33, v30
	v_fma_f32 v29, -v29, v32, v31
	v_div_fmas_f32 v29, v29, v30, v32
	v_div_fixup_f32 v28, v29, v28, 1.0
	v_pk_mul_f32 v[12:13], v[12:13], v[28:29] op_sel_hi:[1,0]
	v_pk_mul_f32 v[14:15], v[14:15], v[28:29] op_sel_hi:[1,0]
	v_pk_mul_f32 v[30:31], v[8:9], v[28:29] op_sel_hi:[1,0]
	v_pk_mul_f32 v[32:33], v[10:11], v[28:29] op_sel_hi:[1,0]
	v_pk_fma_f32 v[10:11], v[126:127], v[14:15], v[16:17]
	v_pk_fma_f32 v[8:9], v[124:125], v[12:13], v[24:25]
	v_pk_fma_f32 v[14:15], v[122:123], v[32:33], v[18:19]
	v_pk_fma_f32 v[12:13], v[120:121], v[30:31], v[26:27]
	global_store_dwordx4 v[20:21], v[8:11], off nt
	global_store_dwordx4 v[20:21], v[12:15], off offset:16 nt
	global_load_dwordx4 v[8:11], v[22:23], off
	v_pk_mul_f32 v[4:5], v[4:5], v[28:29] op_sel_hi:[1,0]
	v_pk_mul_f32 v[6:7], v[6:7], v[28:29] op_sel_hi:[1,0]
	v_pk_mul_f32 v[12:13], v[0:1], v[28:29] op_sel_hi:[1,0]
	v_pk_mul_f32 v[14:15], v[2:3], v[28:29] op_sel_hi:[1,0]
	s_waitcnt vmcnt(0)
	v_lshlrev_b32_e32 v0, 16, v8
	v_and_b32_e32 v1, 0xffff0000, v8
	v_lshlrev_b32_e32 v2, 16, v9
	v_and_b32_e32 v3, 0xffff0000, v9
	v_lshlrev_b32_e32 v8, 16, v10
	v_and_b32_e32 v9, 0xffff0000, v10
	v_lshlrev_b32_e32 v10, 16, v11
	v_and_b32_e32 v11, 0xffff0000, v11
	v_pk_fma_f32 v[2:3], v[118:119], v[6:7], v[2:3]
	v_pk_fma_f32 v[0:1], v[116:117], v[4:5], v[0:1]
	v_pk_fma_f32 v[6:7], v[114:115], v[14:15], v[10:11]
	v_pk_fma_f32 v[4:5], v[112:113], v[12:13], v[8:9]
	global_store_dwordx4 v[20:21], v[0:3], off offset:512 nt
	global_store_dwordx4 v[20:21], v[4:7], off offset:528 nt
	s_barrier
